# remove every s_setprio (GEMM K-loops ran MMA blocks at priority 1); plus earlier: early acquire-inv in barrier, attention K/V staging loads batched, spatial bias loads hoisted, PEER fold LDS staging l
# speedup vs baseline: 1.0054x; 1.0054x over previous
.LBB0_39:
	s_add_u32 s58, s56, 0xfffc0080
	s_addc_u32 s59, s57, -1
	s_add_i32 s77, 0, 0x10000
	s_cmp_eq_u32 s76, 12
	s_cselect_b32 s61, s4, s59
	s_cselect_b32 s60, s5, s58
	s_cselect_b32 s59, s41, s75
	s_cselect_b32 s58, s49, s51
	s_add_i32 s80, 0, 0x14000
	v_add_u32_e32 v68, s77, v250
	v_add_u32_e32 v166, s80, v250
	ds_read_b128 v[40:43], v68
	ds_read_b128 v[48:51], v68 offset:1024
	ds_read_b128 v[60:63], v68 offset:2048
	ds_read_b128 v[68:71], v68 offset:3072
	ds_read_b128 v[146:149], v166
	ds_read_b128 v[150:153], v166 offset:1024
	ds_read_b128 v[154:157], v166 offset:2048
	ds_read_b128 v[166:169], v166 offset:3072
	v_lshl_add_u64 v[202:203], s[56:57], 0, v[162:163]
	s_add_i32 m0, s30, 0xc000
	ds_read_b128 v[170:173], v251
	ds_read_b128 v[174:177], v251 offset:1024
	ds_read_b128 v[178:181], v251 offset:2048
	ds_read_b128 v[182:185], v251 offset:3072
	ds_read_b128 v[186:189], v251 offset:4096
	ds_read_b128 v[190:193], v251 offset:5120
	ds_read_b128 v[194:197], v251 offset:6144
	ds_read_b128 v[198:201], v251 offset:7168
	global_load_lds_dwordx4 v[202:203], off
	v_lshl_add_u64 v[202:203], s[56:57], 0, v[164:165]
	s_add_i32 m0, s30, 0xe000
	s_nop 0
	global_load_lds_dwordx4 v[202:203], off
	s_waitcnt vmcnt(8)
	s_waitcnt lgkmcnt(0)
	s_barrier
	s_waitcnt lgkmcnt(0)
	v_mfma_f32_16x16x32_bf16 v[140:143], v[40:43], v[170:173], v[140:143]
	v_mfma_f32_16x16x32_bf16 v[136:139], v[60:63], v[170:173], v[136:139]
	v_mfma_f32_16x16x32_bf16 v[124:127], v[40:43], v[178:181], v[124:127]
	v_mfma_f32_16x16x32_bf16 v[120:123], v[60:63], v[178:181], v[120:123]
	v_mfma_f32_16x16x32_bf16 v[108:111], v[40:43], v[186:189], v[108:111]
	v_mfma_f32_16x16x32_bf16 v[104:107], v[60:63], v[186:189], v[104:107]
	v_mfma_f32_16x16x32_bf16 v[92:95], v[40:43], v[194:197], v[92:95]
	v_mfma_f32_16x16x32_bf16 v[88:91], v[60:63], v[194:197], v[88:91]
	v_mfma_f32_16x16x32_bf16 v[140:143], v[48:51], v[174:177], v[140:143]
	v_mfma_f32_16x16x32_bf16 v[136:139], v[68:71], v[174:177], v[136:139]
	v_mfma_f32_16x16x32_bf16 v[124:127], v[48:51], v[182:185], v[124:127]
	v_mfma_f32_16x16x32_bf16 v[120:123], v[68:71], v[182:185], v[120:123]
	v_mfma_f32_16x16x32_bf16 v[108:111], v[48:51], v[190:193], v[108:111]
	v_mfma_f32_16x16x32_bf16 v[104:107], v[68:71], v[190:193], v[104:107]
	v_mfma_f32_16x16x32_bf16 v[92:95], v[48:51], v[198:201], v[92:95]
	v_mfma_f32_16x16x32_bf16 v[88:91], v[68:71], v[198:201], v[88:91]
	v_mfma_f32_16x16x32_bf16 v[132:135], v[146:149], v[170:173], v[132:135]
	v_mfma_f32_16x16x32_bf16 v[128:131], v[154:157], v[170:173], v[128:131]
	v_mfma_f32_16x16x32_bf16 v[116:119], v[146:149], v[178:181], v[116:119]
	v_mfma_f32_16x16x32_bf16 v[112:115], v[154:157], v[178:181], v[112:115]
	v_mfma_f32_16x16x32_bf16 v[100:103], v[146:149], v[186:189], v[100:103]
	v_mfma_f32_16x16x32_bf16 v[96:99], v[154:157], v[186:189], v[96:99]
	v_mfma_f32_16x16x32_bf16 v[84:87], v[146:149], v[194:197], v[84:87]
	v_mfma_f32_16x16x32_bf16 v[80:83], v[154:157], v[194:197], v[80:83]
	v_mfma_f32_16x16x32_bf16 v[132:135], v[150:153], v[174:177], v[132:135]
	v_mfma_f32_16x16x32_bf16 v[128:131], v[166:169], v[174:177], v[128:131]
	v_mfma_f32_16x16x32_bf16 v[116:119], v[150:153], v[182:185], v[116:119]
	v_mfma_f32_16x16x32_bf16 v[112:115], v[166:169], v[182:185], v[112:115]
	v_mfma_f32_16x16x32_bf16 v[100:103], v[150:153], v[190:193], v[100:103]
	v_mfma_f32_16x16x32_bf16 v[96:99], v[166:169], v[190:193], v[96:99]
	v_mfma_f32_16x16x32_bf16 v[84:87], v[150:153], v[198:201], v[84:87]
	v_mfma_f32_16x16x32_bf16 v[80:83], v[166:169], v[198:201], v[80:83]
	s_barrier
	s_add_i32 s77, s77, s27
	v_lshl_add_u64 v[202:203], s[58:59], 0, v[144:145]
	s_mov_b32 m0, s77
	ds_read_b128 v[170:173], v251 offset:16384
	ds_read_b128 v[174:177], v251 offset:17408
	ds_read_b128 v[178:181], v251 offset:18432
	ds_read_b128 v[182:185], v251 offset:19456
	ds_read_b128 v[186:189], v251 offset:20480
	ds_read_b128 v[190:193], v251 offset:21504
	ds_read_b128 v[194:197], v251 offset:22528
	ds_read_b128 v[198:201], v251 offset:23552
	global_load_lds_dwordx4 v[202:203], off
	s_add_i32 m0, s77, 0x2000
	s_add_u32 s78, s58, 0x40000
	v_lshl_add_u64 v[204:205], s[58:59], 0, v[160:161]
	s_addc_u32 s79, s59, 0
	s_add_i32 s77, s80, s27
	global_load_lds_dwordx4 v[204:205], off
	v_lshl_add_u64 v[206:207], s[78:79], 0, v[144:145]
	s_mov_b32 m0, s77
	v_lshl_add_u64 v[208:209], s[60:61], 0, v[160:161]
	global_load_lds_dwordx4 v[206:207], off
	v_lshl_add_u64 v[206:207], s[78:79], 0, v[160:161]
	s_add_i32 m0, s77, 0x2000
	s_nop 0
	global_load_lds_dwordx4 v[206:207], off
	v_lshl_add_u64 v[206:207], s[60:61], 0, v[144:145]
	s_mov_b32 m0, s30
	s_nop 0
	global_load_lds_dwordx4 v[206:207], off
	s_mov_b32 m0, s62
	s_nop 0
	global_load_lds_dwordx4 v[208:209], off
	s_waitcnt vmcnt(8)
	s_waitcnt lgkmcnt(0)
	s_barrier
	s_waitcnt lgkmcnt(0)
	v_mfma_f32_16x16x32_bf16 v[76:79], v[40:43], v[170:173], v[76:79]
	v_mfma_f32_16x16x32_bf16 v[72:75], v[60:63], v[170:173], v[72:75]
	v_mfma_f32_16x16x32_bf16 v[52:55], v[40:43], v[178:181], v[52:55]
	v_mfma_f32_16x16x32_bf16 v[44:47], v[60:63], v[178:181], v[44:47]
	v_mfma_f32_16x16x32_bf16 v[28:31], v[40:43], v[186:189], v[28:31]
	v_mfma_f32_16x16x32_bf16 v[24:27], v[60:63], v[186:189], v[24:27]
	v_mfma_f32_16x16x32_bf16 v[12:15], v[40:43], v[194:197], v[12:15]
	v_mfma_f32_16x16x32_bf16 v[8:11], v[60:63], v[194:197], v[8:11]
	v_mfma_f32_16x16x32_bf16 v[76:79], v[48:51], v[174:177], v[76:79]
	v_mfma_f32_16x16x32_bf16 v[72:75], v[68:71], v[174:177], v[72:75]
	v_mfma_f32_16x16x32_bf16 v[52:55], v[48:51], v[182:185], v[52:55]
	v_mfma_f32_16x16x32_bf16 v[44:47], v[68:71], v[182:185], v[44:47]
	v_mfma_f32_16x16x32_bf16 v[28:31], v[48:51], v[190:193], v[28:31]
	v_mfma_f32_16x16x32_bf16 v[24:27], v[68:71], v[190:193], v[24:27]
	v_mfma_f32_16x16x32_bf16 v[12:15], v[48:51], v[198:201], v[12:15]
	v_mfma_f32_16x16x32_bf16 v[8:11], v[68:71], v[198:201], v[8:11]
	v_mfma_f32_16x16x32_bf16 v[36:39], v[146:149], v[178:181], v[36:39]
	v_mfma_f32_16x16x32_bf16 v[32:35], v[154:157], v[178:181], v[32:35]
	v_mfma_f32_16x16x32_bf16 v[20:23], v[146:149], v[186:189], v[20:23]
	v_mfma_f32_16x16x32_bf16 v[16:19], v[154:157], v[186:189], v[16:19]
	v_mfma_f32_16x16x32_bf16 v[4:7], v[146:149], v[194:197], v[4:7]
	v_mfma_f32_16x16x32_bf16 v[0:3], v[154:157], v[194:197], v[0:3]
	v_mfma_f32_16x16x32_bf16 v[40:43], v[146:149], v[170:173], v[64:67]
	v_mfma_f32_16x16x32_bf16 v[48:51], v[154:157], v[170:173], v[56:59]
	v_mfma_f32_16x16x32_bf16 v[36:39], v[150:153], v[182:185], v[36:39]
	v_mfma_f32_16x16x32_bf16 v[32:35], v[166:169], v[182:185], v[32:35]
	v_mfma_f32_16x16x32_bf16 v[20:23], v[150:153], v[190:193], v[20:23]
	v_mfma_f32_16x16x32_bf16 v[16:19], v[166:169], v[190:193], v[16:19]
	v_mfma_f32_16x16x32_bf16 v[4:7], v[150:153], v[198:201], v[4:7]
	v_mfma_f32_16x16x32_bf16 v[0:3], v[166:169], v[198:201], v[0:3]
	v_mfma_f32_16x16x32_bf16 v[40:43], v[150:153], v[174:177], v[40:43]
	v_mfma_f32_16x16x32_bf16 v[48:51], v[166:169], v[174:177], v[48:51]
	s_barrier
	s_add_i32 s77, 0, 0x18000
	s_add_i32 s78, 0, 0x1c000
	v_add_u32_e32 v68, s77, v250
	v_add_u32_e32 v166, s78, v250
	ds_read_b128 v[56:59], v68
	ds_read_b128 v[60:63], v68 offset:1024
	ds_read_b128 v[64:67], v68 offset:2048
	ds_read_b128 v[68:71], v68 offset:3072
	ds_read_b128 v[146:149], v166
	ds_read_b128 v[150:153], v166 offset:1024
	ds_read_b128 v[154:157], v166 offset:2048
	ds_read_b128 v[166:169], v166 offset:3072
	s_add_u32 s60, s60, 0x40000
	s_addc_u32 s61, s61, 0
	s_mov_b32 m0, s63
	v_lshl_add_u64 v[210:211], s[60:61], 0, v[144:145]
	ds_read_b128 v[170:173], v251 offset:32768
	ds_read_b128 v[174:177], v251 offset:33792
	ds_read_b128 v[178:181], v251 offset:34816
	ds_read_b128 v[182:185], v251 offset:35840
	ds_read_b128 v[186:189], v251 offset:36864
	ds_read_b128 v[190:193], v251 offset:37888
	ds_read_b128 v[194:197], v251 offset:38912
	ds_read_b128 v[198:201], v251 offset:39936
	global_load_lds_dwordx4 v[210:211], off
	v_lshl_add_u64 v[210:211], s[60:61], 0, v[160:161]
	s_mov_b32 m0, s64
	s_nop 0
	global_load_lds_dwordx4 v[210:211], off
	s_waitcnt vmcnt(8)
	s_waitcnt lgkmcnt(0)
	s_barrier
	s_waitcnt lgkmcnt(0)
	v_mfma_f32_16x16x32_bf16 v[140:143], v[56:59], v[170:173], v[140:143]
	v_mfma_f32_16x16x32_bf16 v[136:139], v[64:67], v[170:173], v[136:139]
	v_mfma_f32_16x16x32_bf16 v[124:127], v[56:59], v[178:181], v[124:127]
	v_mfma_f32_16x16x32_bf16 v[120:123], v[64:67], v[178:181], v[120:123]
	v_mfma_f32_16x16x32_bf16 v[108:111], v[56:59], v[186:189], v[108:111]
	v_mfma_f32_16x16x32_bf16 v[104:107], v[64:67], v[186:189], v[104:107]
	v_mfma_f32_16x16x32_bf16 v[92:95], v[56:59], v[194:197], v[92:95]
	v_mfma_f32_16x16x32_bf16 v[88:91], v[64:67], v[194:197], v[88:91]
	v_mfma_f32_16x16x32_bf16 v[140:143], v[60:63], v[174:177], v[140:143]
	v_mfma_f32_16x16x32_bf16 v[136:139], v[68:71], v[174:177], v[136:139]
	v_mfma_f32_16x16x32_bf16 v[124:127], v[60:63], v[182:185], v[124:127]
	v_mfma_f32_16x16x32_bf16 v[120:123], v[68:71], v[182:185], v[120:123]
	v_mfma_f32_16x16x32_bf16 v[108:111], v[60:63], v[190:193], v[108:111]
	v_mfma_f32_16x16x32_bf16 v[104:107], v[68:71], v[190:193], v[104:107]
	v_mfma_f32_16x16x32_bf16 v[92:95], v[60:63], v[198:201], v[92:95]
	v_mfma_f32_16x16x32_bf16 v[88:91], v[68:71], v[198:201], v[88:91]
	v_mfma_f32_16x16x32_bf16 v[132:135], v[146:149], v[170:173], v[132:135]
	v_mfma_f32_16x16x32_bf16 v[128:131], v[154:157], v[170:173], v[128:131]
	v_mfma_f32_16x16x32_bf16 v[116:119], v[146:149], v[178:181], v[116:119]
	v_mfma_f32_16x16x32_bf16 v[112:115], v[154:157], v[178:181], v[112:115]
	v_mfma_f32_16x16x32_bf16 v[100:103], v[146:149], v[186:189], v[100:103]
	v_mfma_f32_16x16x32_bf16 v[96:99], v[154:157], v[186:189], v[96:99]
	v_mfma_f32_16x16x32_bf16 v[84:87], v[146:149], v[194:197], v[84:87]
	v_mfma_f32_16x16x32_bf16 v[80:83], v[154:157], v[194:197], v[80:83]
	v_mfma_f32_16x16x32_bf16 v[132:135], v[150:153], v[174:177], v[132:135]
	v_mfma_f32_16x16x32_bf16 v[128:131], v[166:169], v[174:177], v[128:131]
	v_mfma_f32_16x16x32_bf16 v[116:119], v[150:153], v[182:185], v[116:119]
	v_mfma_f32_16x16x32_bf16 v[112:115], v[166:169], v[182:185], v[112:115]
	v_mfma_f32_16x16x32_bf16 v[100:103], v[150:153], v[190:193], v[100:103]
	v_mfma_f32_16x16x32_bf16 v[96:99], v[166:169], v[190:193], v[96:99]
	v_mfma_f32_16x16x32_bf16 v[84:87], v[150:153], v[198:201], v[84:87]
	v_mfma_f32_16x16x32_bf16 v[80:83], v[166:169], v[198:201], v[80:83]
	s_barrier
	s_add_i32 s60, s77, s27
	v_lshl_add_u64 v[202:203], v[202:203], 0, s[20:21]
	s_mov_b32 m0, s60
	ds_read_b128 v[170:173], v251 offset:49152
	ds_read_b128 v[174:177], v251 offset:50176
	ds_read_b128 v[178:181], v251 offset:51200
	ds_read_b128 v[182:185], v251 offset:52224
	ds_read_b128 v[186:189], v251 offset:53248
	ds_read_b128 v[190:193], v251 offset:54272
	ds_read_b128 v[194:197], v251 offset:55296
	ds_read_b128 v[198:201], v251 offset:56320
	global_load_lds_dwordx4 v[202:203], off
	s_add_i32 m0, s60, 0x2000
	s_add_u32 s58, s58, 0x40080
	v_lshl_add_u64 v[202:203], v[204:205], 0, s[20:21]
	s_addc_u32 s59, s59, 0
	s_add_i32 s60, s78, s27
	global_load_lds_dwordx4 v[202:203], off
	v_lshl_add_u64 v[202:203], s[58:59], 0, v[144:145]
	s_mov_b32 m0, s60
	s_nop 0
	global_load_lds_dwordx4 v[202:203], off
	v_lshl_add_u64 v[202:203], s[58:59], 0, v[160:161]
	s_add_i32 m0, s60, 0x2000
	s_nop 0
	global_load_lds_dwordx4 v[202:203], off
	v_lshl_add_u64 v[202:203], v[206:207], 0, s[20:21]
	s_mov_b32 m0, s69
	s_nop 0
	global_load_lds_dwordx4 v[202:203], off
	v_lshl_add_u64 v[202:203], v[208:209], 0, s[20:21]
	s_mov_b32 m0, s70
	s_nop 0
	global_load_lds_dwordx4 v[202:203], off
	s_waitcnt vmcnt(8)
	s_waitcnt lgkmcnt(0)
	s_barrier
	s_waitcnt lgkmcnt(0)
	v_mfma_f32_16x16x32_bf16 v[76:79], v[56:59], v[170:173], v[76:79]
	v_mfma_f32_16x16x32_bf16 v[72:75], v[64:67], v[170:173], v[72:75]
	v_mfma_f32_16x16x32_bf16 v[52:55], v[56:59], v[178:181], v[52:55]
	v_mfma_f32_16x16x32_bf16 v[44:47], v[64:67], v[178:181], v[44:47]
	v_mfma_f32_16x16x32_bf16 v[28:31], v[56:59], v[186:189], v[28:31]
	v_mfma_f32_16x16x32_bf16 v[24:27], v[64:67], v[186:189], v[24:27]
	v_mfma_f32_16x16x32_bf16 v[12:15], v[56:59], v[194:197], v[12:15]
	v_mfma_f32_16x16x32_bf16 v[8:11], v[64:67], v[194:197], v[8:11]
	v_mfma_f32_16x16x32_bf16 v[76:79], v[60:63], v[174:177], v[76:79]
	v_mfma_f32_16x16x32_bf16 v[72:75], v[68:71], v[174:177], v[72:75]
	v_mfma_f32_16x16x32_bf16 v[52:55], v[60:63], v[182:185], v[52:55]
	v_mfma_f32_16x16x32_bf16 v[44:47], v[68:71], v[182:185], v[44:47]
	v_mfma_f32_16x16x32_bf16 v[28:31], v[60:63], v[190:193], v[28:31]
	v_mfma_f32_16x16x32_bf16 v[24:27], v[68:71], v[190:193], v[24:27]
	v_mfma_f32_16x16x32_bf16 v[12:15], v[60:63], v[198:201], v[12:15]
	v_mfma_f32_16x16x32_bf16 v[8:11], v[68:71], v[198:201], v[8:11]
	v_mfma_f32_16x16x32_bf16 v[40:43], v[146:149], v[170:173], v[40:43]
	v_mfma_f32_16x16x32_bf16 v[64:67], v[150:153], v[174:177], v[40:43]
	v_mfma_f32_16x16x32_bf16 v[40:43], v[154:157], v[170:173], v[48:51]
	v_mfma_f32_16x16x32_bf16 v[36:39], v[146:149], v[178:181], v[36:39]
	v_mfma_f32_16x16x32_bf16 v[32:35], v[154:157], v[178:181], v[32:35]
	v_mfma_f32_16x16x32_bf16 v[20:23], v[146:149], v[186:189], v[20:23]
	v_mfma_f32_16x16x32_bf16 v[16:19], v[154:157], v[186:189], v[16:19]
	v_mfma_f32_16x16x32_bf16 v[4:7], v[146:149], v[194:197], v[4:7]
	v_mfma_f32_16x16x32_bf16 v[0:3], v[154:157], v[194:197], v[0:3]
	v_mfma_f32_16x16x32_bf16 v[56:59], v[166:169], v[174:177], v[40:43]
	v_mfma_f32_16x16x32_bf16 v[36:39], v[150:153], v[182:185], v[36:39]
	v_mfma_f32_16x16x32_bf16 v[32:35], v[166:169], v[182:185], v[32:35]
	v_mfma_f32_16x16x32_bf16 v[20:23], v[150:153], v[190:193], v[20:23]
	v_mfma_f32_16x16x32_bf16 v[16:19], v[166:169], v[190:193], v[16:19]
	v_mfma_f32_16x16x32_bf16 v[4:7], v[150:153], v[198:201], v[4:7]
	v_mfma_f32_16x16x32_bf16 v[0:3], v[166:169], v[198:201], v[0:3]
	s_barrier
	s_add_i32 s76, s76, 2
	s_add_u32 s56, s56, 0x100
	s_addc_u32 s57, s57, 0
	s_add_u32 s51, s51, 0x100
	s_addc_u32 s75, s75, 0
	s_cmp_gt_u32 s76, 13
	s_cbranch_scc0 .LBB0_39
	s_and_b64 vcc, exec, s[44:45]
	s_cbranch_vccz .LBB0_42
	s_barrier

.LBB0_346:
	s_add_u32 s46, s44, 0xfffc0080
	s_addc_u32 s47, s45, -1
	s_add_i32 s63, 0, 0x10000
	s_cmp_eq_u32 s62, 12
	s_cselect_b32 s49, s4, s47
	s_cselect_b32 s48, s5, s46
	v_add_u32_e32 v142, s63, v136
	s_cselect_b32 s47, s25, s61
	s_cselect_b32 s46, s39, s60
	s_add_i32 s68, 0, 0x14000
	ds_read_b128 v[138:141], v142
	ds_read_b128 v[146:149], v142 offset:1024
	ds_read_b128 v[150:153], v142 offset:2048
	ds_read_b128 v[154:157], v142 offset:3072
	v_add_u32_e32 v142, s68, v136
	ds_read_b128 v[160:163], v142
	ds_read_b128 v[164:167], v142 offset:1024
	ds_read_b128 v[168:171], v142 offset:2048
	ds_read_b128 v[172:175], v142 offset:3072
	v_lshl_add_u64 v[142:143], s[44:45], 0, v[130:131]
	s_add_i32 m0, s17, 0xc000
	ds_read_b128 v[176:179], v137
	ds_read_b128 v[180:183], v137 offset:1024
	ds_read_b128 v[184:187], v137 offset:2048
	ds_read_b128 v[188:191], v137 offset:3072
	ds_read_b128 v[192:195], v137 offset:4096
	ds_read_b128 v[196:199], v137 offset:5120
	ds_read_b128 v[200:203], v137 offset:6144
	ds_read_b128 v[204:207], v137 offset:7168
	global_load_lds_dwordx4 v[142:143], off
	v_lshl_add_u64 v[142:143], s[44:45], 0, v[132:133]
	s_add_i32 m0, s17, 0xe000
	s_nop 0
	global_load_lds_dwordx4 v[142:143], off
	s_waitcnt vmcnt(8)
	s_waitcnt lgkmcnt(0)
	s_barrier
	s_waitcnt lgkmcnt(0)
	v_mfma_f32_16x16x32_bf16 v[124:127], v[138:141], v[176:179], v[124:127]
	v_mfma_f32_16x16x32_bf16 v[120:123], v[150:153], v[176:179], v[120:123]
	v_mfma_f32_16x16x32_bf16 v[116:119], v[138:141], v[184:187], v[116:119]
	v_mfma_f32_16x16x32_bf16 v[108:111], v[150:153], v[184:187], v[108:111]
	v_mfma_f32_16x16x32_bf16 v[92:95], v[138:141], v[192:195], v[92:95]
	v_mfma_f32_16x16x32_bf16 v[84:87], v[150:153], v[192:195], v[84:87]
	v_mfma_f32_16x16x32_bf16 v[60:63], v[138:141], v[200:203], v[60:63]
	v_mfma_f32_16x16x32_bf16 v[52:55], v[150:153], v[200:203], v[52:55]
	v_mfma_f32_16x16x32_bf16 v[124:127], v[146:149], v[180:183], v[124:127]
	v_mfma_f32_16x16x32_bf16 v[120:123], v[154:157], v[180:183], v[120:123]
	v_mfma_f32_16x16x32_bf16 v[116:119], v[146:149], v[188:191], v[116:119]
	v_mfma_f32_16x16x32_bf16 v[108:111], v[154:157], v[188:191], v[108:111]
	v_mfma_f32_16x16x32_bf16 v[92:95], v[146:149], v[196:199], v[92:95]
	v_mfma_f32_16x16x32_bf16 v[84:87], v[154:157], v[196:199], v[84:87]
	v_mfma_f32_16x16x32_bf16 v[60:63], v[146:149], v[204:207], v[60:63]
	v_mfma_f32_16x16x32_bf16 v[52:55], v[154:157], v[204:207], v[52:55]
	v_mfma_f32_16x16x32_bf16 v[112:115], v[160:163], v[176:179], v[112:115]
	v_mfma_f32_16x16x32_bf16 v[104:107], v[168:171], v[176:179], v[104:107]
	v_mfma_f32_16x16x32_bf16 v[88:91], v[160:163], v[184:187], v[88:91]
	v_mfma_f32_16x16x32_bf16 v[80:83], v[168:171], v[184:187], v[80:83]
	v_mfma_f32_16x16x32_bf16 v[56:59], v[160:163], v[192:195], v[56:59]
	v_mfma_f32_16x16x32_bf16 v[48:51], v[168:171], v[192:195], v[48:51]
	v_mfma_f32_16x16x32_bf16 v[28:31], v[160:163], v[200:203], v[28:31]
	v_mfma_f32_16x16x32_bf16 v[24:27], v[168:171], v[200:203], v[24:27]
	v_mfma_f32_16x16x32_bf16 v[112:115], v[164:167], v[180:183], v[112:115]
	v_mfma_f32_16x16x32_bf16 v[104:107], v[172:175], v[180:183], v[104:107]
	v_mfma_f32_16x16x32_bf16 v[88:91], v[164:167], v[188:191], v[88:91]
	v_mfma_f32_16x16x32_bf16 v[80:83], v[172:175], v[188:191], v[80:83]
	v_mfma_f32_16x16x32_bf16 v[56:59], v[164:167], v[196:199], v[56:59]
	v_mfma_f32_16x16x32_bf16 v[48:51], v[172:175], v[196:199], v[48:51]
	v_mfma_f32_16x16x32_bf16 v[28:31], v[164:167], v[204:207], v[28:31]
	v_mfma_f32_16x16x32_bf16 v[24:27], v[172:175], v[204:207], v[24:27]
	s_barrier
	s_add_i32 s63, s63, s27
	v_lshl_add_u64 v[142:143], s[46:47], 0, v[144:145]
	s_mov_b32 m0, s63
	ds_read_b128 v[176:179], v137 offset:16384
	ds_read_b128 v[180:183], v137 offset:17408
	ds_read_b128 v[184:187], v137 offset:18432
	ds_read_b128 v[188:191], v137 offset:19456
	ds_read_b128 v[192:195], v137 offset:20480
	ds_read_b128 v[196:199], v137 offset:21504
	ds_read_b128 v[200:203], v137 offset:22528
	ds_read_b128 v[204:207], v137 offset:23552
	global_load_lds_dwordx4 v[142:143], off
	s_add_i32 m0, s63, 0x2000
	s_add_u32 s64, s46, 0x40000
	v_lshl_add_u64 v[208:209], s[46:47], 0, v[128:129]
	s_addc_u32 s65, s47, 0
	s_add_i32 s63, s68, s27
	global_load_lds_dwordx4 v[208:209], off
	v_lshl_add_u64 v[210:211], s[64:65], 0, v[144:145]
	s_mov_b32 m0, s63
	v_lshl_add_u64 v[212:213], s[48:49], 0, v[128:129]
	global_load_lds_dwordx4 v[210:211], off
	v_lshl_add_u64 v[210:211], s[64:65], 0, v[128:129]
	s_add_i32 m0, s63, 0x2000
	s_nop 0
	global_load_lds_dwordx4 v[210:211], off
	v_lshl_add_u64 v[210:211], s[48:49], 0, v[144:145]
	s_mov_b32 m0, s17
	s_nop 0
	global_load_lds_dwordx4 v[210:211], off
	s_mov_b32 m0, s50
	s_nop 0
	global_load_lds_dwordx4 v[212:213], off
	s_waitcnt vmcnt(8)
	s_waitcnt lgkmcnt(0)
	s_barrier
	s_waitcnt lgkmcnt(0)
	v_mfma_f32_16x16x32_bf16 v[100:103], v[138:141], v[176:179], v[100:103]
	v_mfma_f32_16x16x32_bf16 v[96:99], v[150:153], v[176:179], v[96:99]
	v_mfma_f32_16x16x32_bf16 v[76:79], v[138:141], v[184:187], v[76:79]
	v_mfma_f32_16x16x32_bf16 v[68:71], v[150:153], v[184:187], v[68:71]
	v_mfma_f32_16x16x32_bf16 v[44:47], v[138:141], v[192:195], v[44:47]
	v_mfma_f32_16x16x32_bf16 v[36:39], v[150:153], v[192:195], v[36:39]
	v_mfma_f32_16x16x32_bf16 v[20:23], v[138:141], v[200:203], v[20:23]
	v_mfma_f32_16x16x32_bf16 v[12:15], v[150:153], v[200:203], v[12:15]
	v_mfma_f32_16x16x32_bf16 v[100:103], v[146:149], v[180:183], v[100:103]
	v_mfma_f32_16x16x32_bf16 v[96:99], v[154:157], v[180:183], v[96:99]
	v_mfma_f32_16x16x32_bf16 v[76:79], v[146:149], v[188:191], v[76:79]
	v_mfma_f32_16x16x32_bf16 v[68:71], v[154:157], v[188:191], v[68:71]
	v_mfma_f32_16x16x32_bf16 v[44:47], v[146:149], v[196:199], v[44:47]
	v_mfma_f32_16x16x32_bf16 v[36:39], v[154:157], v[196:199], v[36:39]
	v_mfma_f32_16x16x32_bf16 v[20:23], v[146:149], v[204:207], v[20:23]
	v_mfma_f32_16x16x32_bf16 v[12:15], v[154:157], v[204:207], v[12:15]
	v_mfma_f32_16x16x32_bf16 v[72:75], v[160:163], v[176:179], v[72:75]
	v_mfma_f32_16x16x32_bf16 v[64:67], v[168:171], v[176:179], v[64:67]
	v_mfma_f32_16x16x32_bf16 v[40:43], v[160:163], v[184:187], v[40:43]
	v_mfma_f32_16x16x32_bf16 v[32:35], v[168:171], v[184:187], v[32:35]
	v_mfma_f32_16x16x32_bf16 v[16:19], v[160:163], v[192:195], v[16:19]
	v_mfma_f32_16x16x32_bf16 v[8:11], v[168:171], v[192:195], v[8:11]
	v_mfma_f32_16x16x32_bf16 v[4:7], v[160:163], v[200:203], v[4:7]
	v_mfma_f32_16x16x32_bf16 v[0:3], v[168:171], v[200:203], v[0:3]
	v_mfma_f32_16x16x32_bf16 v[72:75], v[164:167], v[180:183], v[72:75]
	v_mfma_f32_16x16x32_bf16 v[64:67], v[172:175], v[180:183], v[64:67]
	v_mfma_f32_16x16x32_bf16 v[40:43], v[164:167], v[188:191], v[40:43]
	v_mfma_f32_16x16x32_bf16 v[32:35], v[172:175], v[188:191], v[32:35]
	v_mfma_f32_16x16x32_bf16 v[16:19], v[164:167], v[196:199], v[16:19]
	v_mfma_f32_16x16x32_bf16 v[8:11], v[172:175], v[196:199], v[8:11]
	v_mfma_f32_16x16x32_bf16 v[4:7], v[164:167], v[204:207], v[4:7]
	v_mfma_f32_16x16x32_bf16 v[0:3], v[172:175], v[204:207], v[0:3]
	s_barrier
	s_add_i32 s63, 0, 0x18000
	s_add_i32 s64, 0, 0x1c000
	v_add_u32_e32 v154, s63, v136
	v_add_u32_e32 v159, s64, v136
	ds_read_b128 v[138:141], v154
	ds_read_b128 v[146:149], v154 offset:1024
	ds_read_b128 v[150:153], v154 offset:2048
	ds_read_b128 v[154:157], v154 offset:3072
	ds_read_b128 v[160:163], v159
	ds_read_b128 v[164:167], v159 offset:1024
	ds_read_b128 v[168:171], v159 offset:2048
	ds_read_b128 v[172:175], v159 offset:3072
	s_add_u32 s48, s48, 0x40000
	s_addc_u32 s49, s49, 0
	s_mov_b32 m0, s51
	v_lshl_add_u64 v[214:215], s[48:49], 0, v[144:145]
	ds_read_b128 v[176:179], v137 offset:32768
	ds_read_b128 v[180:183], v137 offset:33792
	ds_read_b128 v[184:187], v137 offset:34816
	ds_read_b128 v[188:191], v137 offset:35840
	ds_read_b128 v[192:195], v137 offset:36864
	ds_read_b128 v[196:199], v137 offset:37888
	ds_read_b128 v[200:203], v137 offset:38912
	ds_read_b128 v[204:207], v137 offset:39936
	global_load_lds_dwordx4 v[214:215], off
	v_lshl_add_u64 v[214:215], s[48:49], 0, v[128:129]
	s_mov_b32 m0, s52
	s_nop 0
	global_load_lds_dwordx4 v[214:215], off
	s_waitcnt vmcnt(8)
	s_waitcnt lgkmcnt(0)
	s_barrier
	s_waitcnt lgkmcnt(0)
	v_mfma_f32_16x16x32_bf16 v[124:127], v[138:141], v[176:179], v[124:127]
	v_mfma_f32_16x16x32_bf16 v[120:123], v[150:153], v[176:179], v[120:123]
	v_mfma_f32_16x16x32_bf16 v[116:119], v[138:141], v[184:187], v[116:119]
	v_mfma_f32_16x16x32_bf16 v[108:111], v[150:153], v[184:187], v[108:111]
	v_mfma_f32_16x16x32_bf16 v[92:95], v[138:141], v[192:195], v[92:95]
	v_mfma_f32_16x16x32_bf16 v[84:87], v[150:153], v[192:195], v[84:87]
	v_mfma_f32_16x16x32_bf16 v[60:63], v[138:141], v[200:203], v[60:63]
	v_mfma_f32_16x16x32_bf16 v[52:55], v[150:153], v[200:203], v[52:55]
	v_mfma_f32_16x16x32_bf16 v[124:127], v[146:149], v[180:183], v[124:127]
	v_mfma_f32_16x16x32_bf16 v[120:123], v[154:157], v[180:183], v[120:123]
	v_mfma_f32_16x16x32_bf16 v[116:119], v[146:149], v[188:191], v[116:119]
	v_mfma_f32_16x16x32_bf16 v[108:111], v[154:157], v[188:191], v[108:111]
	v_mfma_f32_16x16x32_bf16 v[92:95], v[146:149], v[196:199], v[92:95]
	v_mfma_f32_16x16x32_bf16 v[84:87], v[154:157], v[196:199], v[84:87]
	v_mfma_f32_16x16x32_bf16 v[60:63], v[146:149], v[204:207], v[60:63]
	v_mfma_f32_16x16x32_bf16 v[52:55], v[154:157], v[204:207], v[52:55]
	v_mfma_f32_16x16x32_bf16 v[112:115], v[160:163], v[176:179], v[112:115]
	v_mfma_f32_16x16x32_bf16 v[104:107], v[168:171], v[176:179], v[104:107]
	v_mfma_f32_16x16x32_bf16 v[88:91], v[160:163], v[184:187], v[88:91]
	v_mfma_f32_16x16x32_bf16 v[80:83], v[168:171], v[184:187], v[80:83]
	v_mfma_f32_16x16x32_bf16 v[56:59], v[160:163], v[192:195], v[56:59]
	v_mfma_f32_16x16x32_bf16 v[48:51], v[168:171], v[192:195], v[48:51]
	v_mfma_f32_16x16x32_bf16 v[28:31], v[160:163], v[200:203], v[28:31]
	v_mfma_f32_16x16x32_bf16 v[24:27], v[168:171], v[200:203], v[24:27]
	v_mfma_f32_16x16x32_bf16 v[112:115], v[164:167], v[180:183], v[112:115]
	v_mfma_f32_16x16x32_bf16 v[104:107], v[172:175], v[180:183], v[104:107]
	v_mfma_f32_16x16x32_bf16 v[88:91], v[164:167], v[188:191], v[88:91]
	v_mfma_f32_16x16x32_bf16 v[80:83], v[172:175], v[188:191], v[80:83]
	v_mfma_f32_16x16x32_bf16 v[56:59], v[164:167], v[196:199], v[56:59]
	v_mfma_f32_16x16x32_bf16 v[48:51], v[172:175], v[196:199], v[48:51]
	v_mfma_f32_16x16x32_bf16 v[28:31], v[164:167], v[204:207], v[28:31]
	v_mfma_f32_16x16x32_bf16 v[24:27], v[172:175], v[204:207], v[24:27]
	s_barrier
	s_add_i32 s48, s63, s27
	v_lshl_add_u64 v[142:143], v[142:143], 0, s[20:21]
	s_mov_b32 m0, s48
	ds_read_b128 v[176:179], v137 offset:49152
	ds_read_b128 v[180:183], v137 offset:50176
	ds_read_b128 v[184:187], v137 offset:51200
	ds_read_b128 v[188:191], v137 offset:52224
	ds_read_b128 v[192:195], v137 offset:53248
	ds_read_b128 v[196:199], v137 offset:54272
	ds_read_b128 v[200:203], v137 offset:55296
	ds_read_b128 v[204:207], v137 offset:56320
	global_load_lds_dwordx4 v[142:143], off
	s_add_i32 m0, s48, 0x2000
	s_add_u32 s46, s46, 0x40080
	v_lshl_add_u64 v[142:143], v[208:209], 0, s[20:21]
	s_addc_u32 s47, s47, 0
	s_add_i32 s48, s64, s27
	global_load_lds_dwordx4 v[142:143], off
	v_lshl_add_u64 v[142:143], s[46:47], 0, v[144:145]
	s_mov_b32 m0, s48
	s_nop 0
	global_load_lds_dwordx4 v[142:143], off
	v_lshl_add_u64 v[142:143], s[46:47], 0, v[128:129]
	s_add_i32 m0, s48, 0x2000
	s_nop 0
	global_load_lds_dwordx4 v[142:143], off
	v_lshl_add_u64 v[142:143], v[210:211], 0, s[20:21]
	s_mov_b32 m0, s55
	s_nop 0
	global_load_lds_dwordx4 v[142:143], off
	v_lshl_add_u64 v[142:143], v[212:213], 0, s[20:21]
	s_mov_b32 m0, s56
	s_nop 0
	global_load_lds_dwordx4 v[142:143], off
	s_waitcnt vmcnt(8)
	s_waitcnt lgkmcnt(0)
	s_barrier
	s_waitcnt lgkmcnt(0)
	v_mfma_f32_16x16x32_bf16 v[100:103], v[138:141], v[176:179], v[100:103]
	v_mfma_f32_16x16x32_bf16 v[96:99], v[150:153], v[176:179], v[96:99]
	v_mfma_f32_16x16x32_bf16 v[76:79], v[138:141], v[184:187], v[76:79]
	v_mfma_f32_16x16x32_bf16 v[68:71], v[150:153], v[184:187], v[68:71]
	v_mfma_f32_16x16x32_bf16 v[44:47], v[138:141], v[192:195], v[44:47]
	v_mfma_f32_16x16x32_bf16 v[36:39], v[150:153], v[192:195], v[36:39]
	v_mfma_f32_16x16x32_bf16 v[20:23], v[138:141], v[200:203], v[20:23]
	v_mfma_f32_16x16x32_bf16 v[12:15], v[150:153], v[200:203], v[12:15]
	v_mfma_f32_16x16x32_bf16 v[100:103], v[146:149], v[180:183], v[100:103]
	v_mfma_f32_16x16x32_bf16 v[96:99], v[154:157], v[180:183], v[96:99]
	v_mfma_f32_16x16x32_bf16 v[76:79], v[146:149], v[188:191], v[76:79]
	v_mfma_f32_16x16x32_bf16 v[68:71], v[154:157], v[188:191], v[68:71]
	v_mfma_f32_16x16x32_bf16 v[44:47], v[146:149], v[196:199], v[44:47]
	v_mfma_f32_16x16x32_bf16 v[36:39], v[154:157], v[196:199], v[36:39]
	v_mfma_f32_16x16x32_bf16 v[20:23], v[146:149], v[204:207], v[20:23]
	v_mfma_f32_16x16x32_bf16 v[12:15], v[154:157], v[204:207], v[12:15]
	v_mfma_f32_16x16x32_bf16 v[72:75], v[160:163], v[176:179], v[72:75]
	v_mfma_f32_16x16x32_bf16 v[64:67], v[168:171], v[176:179], v[64:67]
	v_mfma_f32_16x16x32_bf16 v[40:43], v[160:163], v[184:187], v[40:43]
	v_mfma_f32_16x16x32_bf16 v[32:35], v[168:171], v[184:187], v[32:35]
	v_mfma_f32_16x16x32_bf16 v[16:19], v[160:163], v[192:195], v[16:19]
	v_mfma_f32_16x16x32_bf16 v[8:11], v[168:171], v[192:195], v[8:11]
	v_mfma_f32_16x16x32_bf16 v[4:7], v[160:163], v[200:203], v[4:7]
	v_mfma_f32_16x16x32_bf16 v[0:3], v[168:171], v[200:203], v[0:3]
	v_mfma_f32_16x16x32_bf16 v[72:75], v[164:167], v[180:183], v[72:75]
	v_mfma_f32_16x16x32_bf16 v[64:67], v[172:175], v[180:183], v[64:67]
	v_mfma_f32_16x16x32_bf16 v[40:43], v[164:167], v[188:191], v[40:43]
	v_mfma_f32_16x16x32_bf16 v[32:35], v[172:175], v[188:191], v[32:35]
	v_mfma_f32_16x16x32_bf16 v[16:19], v[164:167], v[196:199], v[16:19]
	v_mfma_f32_16x16x32_bf16 v[8:11], v[172:175], v[196:199], v[8:11]
	v_mfma_f32_16x16x32_bf16 v[4:7], v[164:167], v[204:207], v[4:7]
	v_mfma_f32_16x16x32_bf16 v[0:3], v[172:175], v[204:207], v[0:3]
	s_barrier
	s_add_i32 s62, s62, 2
	s_add_u32 s44, s44, 0x100
	s_addc_u32 s45, s45, 0
	s_add_u32 s60, s60, 0x100
	s_addc_u32 s61, s61, 0
	s_cmp_gt_u32 s62, 13
	s_cbranch_scc0 .LBB0_346
	s_and_b64 vcc, exec, s[12:13]
	s_cbranch_vccz .LBB0_349
	s_barrier

.LBB0_437:
	s_add_i32 s50, s48, 2
	s_add_u32 s51, s40, 0x80
	s_addc_u32 s49, s41, 0
	s_add_i32 s76, 0, 0x10000
	s_cmp_eq_u32 s64, s48
	s_cselect_b32 s49, s45, s49
	s_cselect_b32 s48, s44, s51
	s_cselect_b32 s75, s47, s5
	s_cselect_b32 s74, s46, s4
	s_add_i32 s51, 0, 0x14000
	v_add_u32_e32 v120, s76, v201
	v_add_u32_e32 v166, s51, v201
	ds_read_b128 v[108:111], v120
	ds_read_b128 v[112:115], v120 offset:1024
	ds_read_b128 v[116:119], v120 offset:2048
	ds_read_b128 v[120:123], v120 offset:3072
	ds_read_b128 v[146:149], v166
	ds_read_b128 v[150:153], v166 offset:1024
	ds_read_b128 v[154:157], v166 offset:2048
	ds_read_b128 v[166:169], v166 offset:3072
	v_lshl_add_u64 v[198:199], s[40:41], 0, v[162:163]
	s_add_i32 m0, s55, 0xc000
	ds_read_b128 v[170:173], v202
	ds_read_b128 v[174:177], v202 offset:1024
	ds_read_b128 v[178:181], v202 offset:2048
	ds_read_b128 v[182:185], v202 offset:3072
	ds_read_b128 v[186:189], v202 offset:4096
	ds_read_b128 v[190:193], v202 offset:5120
	ds_read_b128 v[194:197], v202 offset:6144
	ds_read_b128 v[204:207], v202 offset:7168
	global_load_lds_dwordx4 v[198:199], off
	v_lshl_add_u64 v[198:199], s[40:41], 0, v[164:165]
	s_add_i32 m0, s55, 0xe000
	s_nop 0
	global_load_lds_dwordx4 v[198:199], off
	s_waitcnt vmcnt(8)
	s_waitcnt lgkmcnt(0)
	s_barrier
	s_waitcnt lgkmcnt(0)
	v_mfma_f32_16x16x32_bf16 v[140:143], v[108:111], v[170:173], v[140:143]
	v_mfma_f32_16x16x32_bf16 v[136:139], v[116:119], v[170:173], v[136:139]
	v_mfma_f32_16x16x32_bf16 v[132:135], v[108:111], v[178:181], v[132:135]
	v_mfma_f32_16x16x32_bf16 v[104:107], v[116:119], v[178:181], v[104:107]
	v_mfma_f32_16x16x32_bf16 v[96:99], v[108:111], v[186:189], v[96:99]
	v_mfma_f32_16x16x32_bf16 v[88:91], v[116:119], v[186:189], v[88:91]
	v_mfma_f32_16x16x32_bf16 v[80:83], v[108:111], v[194:197], v[80:83]
	v_mfma_f32_16x16x32_bf16 v[72:75], v[116:119], v[194:197], v[72:75]
	v_mfma_f32_16x16x32_bf16 v[140:143], v[112:115], v[174:177], v[140:143]
	v_mfma_f32_16x16x32_bf16 v[136:139], v[120:123], v[174:177], v[136:139]
	v_mfma_f32_16x16x32_bf16 v[132:135], v[112:115], v[182:185], v[132:135]
	v_mfma_f32_16x16x32_bf16 v[104:107], v[120:123], v[182:185], v[104:107]
	v_mfma_f32_16x16x32_bf16 v[96:99], v[112:115], v[190:193], v[96:99]
	v_mfma_f32_16x16x32_bf16 v[88:91], v[120:123], v[190:193], v[88:91]
	v_mfma_f32_16x16x32_bf16 v[80:83], v[112:115], v[204:207], v[80:83]
	v_mfma_f32_16x16x32_bf16 v[72:75], v[120:123], v[204:207], v[72:75]
	v_mfma_f32_16x16x32_bf16 v[128:131], v[146:149], v[170:173], v[128:131]
	v_mfma_f32_16x16x32_bf16 v[124:127], v[154:157], v[170:173], v[124:127]
	v_mfma_f32_16x16x32_bf16 v[100:103], v[146:149], v[178:181], v[100:103]
	v_mfma_f32_16x16x32_bf16 v[92:95], v[154:157], v[178:181], v[92:95]
	v_mfma_f32_16x16x32_bf16 v[84:87], v[146:149], v[186:189], v[84:87]
	v_mfma_f32_16x16x32_bf16 v[76:79], v[154:157], v[186:189], v[76:79]
	v_mfma_f32_16x16x32_bf16 v[68:71], v[146:149], v[194:197], v[68:71]
	v_mfma_f32_16x16x32_bf16 v[64:67], v[154:157], v[194:197], v[64:67]
	v_mfma_f32_16x16x32_bf16 v[128:131], v[150:153], v[174:177], v[128:131]
	v_mfma_f32_16x16x32_bf16 v[124:127], v[166:169], v[174:177], v[124:127]
	v_mfma_f32_16x16x32_bf16 v[100:103], v[150:153], v[182:185], v[100:103]
	v_mfma_f32_16x16x32_bf16 v[92:95], v[166:169], v[182:185], v[92:95]
	v_mfma_f32_16x16x32_bf16 v[84:87], v[150:153], v[190:193], v[84:87]
	v_mfma_f32_16x16x32_bf16 v[76:79], v[166:169], v[190:193], v[76:79]
	v_mfma_f32_16x16x32_bf16 v[68:71], v[150:153], v[204:207], v[68:71]
	v_mfma_f32_16x16x32_bf16 v[64:67], v[166:169], v[204:207], v[64:67]
	s_barrier
	s_add_i32 s76, s76, s52
	v_lshl_add_u64 v[198:199], s[74:75], 0, v[144:145]
	s_mov_b32 m0, s76
	ds_read_b128 v[170:173], v202 offset:16384
	ds_read_b128 v[174:177], v202 offset:17408
	ds_read_b128 v[178:181], v202 offset:18432
	ds_read_b128 v[182:185], v202 offset:19456
	ds_read_b128 v[186:189], v202 offset:20480
	ds_read_b128 v[190:193], v202 offset:21504
	ds_read_b128 v[194:197], v202 offset:22528
	ds_read_b128 v[204:207], v202 offset:23552
	global_load_lds_dwordx4 v[198:199], off
	s_add_i32 m0, s76, 0x2000
	v_lshl_add_u64 v[208:209], s[74:75], 0, v[160:161]
	s_add_u32 s74, s74, s30
	s_addc_u32 s75, s75, 0
	s_add_i32 s51, s51, s52
	global_load_lds_dwordx4 v[208:209], off
	v_lshl_add_u64 v[210:211], s[74:75], 0, v[144:145]
	s_mov_b32 m0, s51
	v_lshl_add_u64 v[212:213], s[74:75], 0, v[160:161]
	global_load_lds_dwordx4 v[210:211], off
	s_add_i32 m0, s51, 0x2000
	v_lshl_add_u64 v[214:215], s[48:49], 0, v[144:145]
	global_load_lds_dwordx4 v[212:213], off
	s_mov_b32 m0, s55
	v_lshl_add_u64 v[216:217], s[48:49], 0, v[160:161]
	global_load_lds_dwordx4 v[214:215], off
	s_mov_b32 m0, s56
	s_nop 0
	global_load_lds_dwordx4 v[216:217], off
	s_waitcnt vmcnt(8)
	s_waitcnt lgkmcnt(0)
	s_barrier
	s_waitcnt lgkmcnt(0)
	v_mfma_f32_16x16x32_bf16 v[60:63], v[108:111], v[170:173], v[60:63]
	v_mfma_f32_16x16x32_bf16 v[56:59], v[116:119], v[170:173], v[56:59]
	v_mfma_f32_16x16x32_bf16 v[48:51], v[108:111], v[178:181], v[48:51]
	v_mfma_f32_16x16x32_bf16 v[40:43], v[116:119], v[178:181], v[40:43]
	v_mfma_f32_16x16x32_bf16 v[32:35], v[108:111], v[186:189], v[32:35]
	v_mfma_f32_16x16x32_bf16 v[24:27], v[116:119], v[186:189], v[24:27]
	v_mfma_f32_16x16x32_bf16 v[16:19], v[108:111], v[194:197], v[16:19]
	v_mfma_f32_16x16x32_bf16 v[8:11], v[116:119], v[194:197], v[8:11]
	v_mfma_f32_16x16x32_bf16 v[60:63], v[112:115], v[174:177], v[60:63]
	v_mfma_f32_16x16x32_bf16 v[56:59], v[120:123], v[174:177], v[56:59]
	v_mfma_f32_16x16x32_bf16 v[48:51], v[112:115], v[182:185], v[48:51]
	v_mfma_f32_16x16x32_bf16 v[40:43], v[120:123], v[182:185], v[40:43]
	v_mfma_f32_16x16x32_bf16 v[32:35], v[112:115], v[190:193], v[32:35]
	v_mfma_f32_16x16x32_bf16 v[24:27], v[120:123], v[190:193], v[24:27]
	v_mfma_f32_16x16x32_bf16 v[16:19], v[112:115], v[204:207], v[16:19]
	v_mfma_f32_16x16x32_bf16 v[8:11], v[120:123], v[204:207], v[8:11]
	v_mfma_f32_16x16x32_bf16 v[52:55], v[146:149], v[170:173], v[52:55]
	v_mfma_f32_16x16x32_bf16 v[44:47], v[154:157], v[170:173], v[44:47]
	v_mfma_f32_16x16x32_bf16 v[36:39], v[146:149], v[178:181], v[36:39]
	v_mfma_f32_16x16x32_bf16 v[28:31], v[154:157], v[178:181], v[28:31]
	v_mfma_f32_16x16x32_bf16 v[20:23], v[146:149], v[186:189], v[20:23]
	v_mfma_f32_16x16x32_bf16 v[12:15], v[154:157], v[186:189], v[12:15]
	v_mfma_f32_16x16x32_bf16 v[4:7], v[146:149], v[194:197], v[4:7]
	v_mfma_f32_16x16x32_bf16 v[0:3], v[154:157], v[194:197], v[0:3]
	v_mfma_f32_16x16x32_bf16 v[52:55], v[150:153], v[174:177], v[52:55]
	v_mfma_f32_16x16x32_bf16 v[44:47], v[166:169], v[174:177], v[44:47]
	v_mfma_f32_16x16x32_bf16 v[36:39], v[150:153], v[182:185], v[36:39]
	v_mfma_f32_16x16x32_bf16 v[28:31], v[166:169], v[182:185], v[28:31]
	v_mfma_f32_16x16x32_bf16 v[20:23], v[150:153], v[190:193], v[20:23]
	v_mfma_f32_16x16x32_bf16 v[12:15], v[166:169], v[190:193], v[12:15]
	v_mfma_f32_16x16x32_bf16 v[4:7], v[150:153], v[204:207], v[4:7]
	v_mfma_f32_16x16x32_bf16 v[0:3], v[166:169], v[204:207], v[0:3]
	s_barrier
	s_add_i32 s51, 0, 0x18000
	s_add_i32 s74, 0, 0x1c000
	v_add_u32_e32 v120, s51, v201
	v_add_u32_e32 v166, s74, v201
	ds_read_b128 v[108:111], v120
	ds_read_b128 v[112:115], v120 offset:1024
	ds_read_b128 v[116:119], v120 offset:2048
	ds_read_b128 v[120:123], v120 offset:3072
	ds_read_b128 v[146:149], v166
	ds_read_b128 v[150:153], v166 offset:1024
	ds_read_b128 v[154:157], v166 offset:2048
	ds_read_b128 v[166:169], v166 offset:3072
	s_add_u32 s48, s48, s30
	s_addc_u32 s49, s49, 0
	s_mov_b32 m0, s57
	v_lshl_add_u64 v[218:219], s[48:49], 0, v[144:145]
	ds_read_b128 v[170:173], v202 offset:32768
	ds_read_b128 v[174:177], v202 offset:33792
	ds_read_b128 v[178:181], v202 offset:34816
	ds_read_b128 v[182:185], v202 offset:35840
	ds_read_b128 v[186:189], v202 offset:36864
	ds_read_b128 v[190:193], v202 offset:37888
	ds_read_b128 v[194:197], v202 offset:38912
	ds_read_b128 v[204:207], v202 offset:39936
	global_load_lds_dwordx4 v[218:219], off
	v_lshl_add_u64 v[218:219], s[48:49], 0, v[160:161]
	s_mov_b32 m0, s58
	s_nop 0
	global_load_lds_dwordx4 v[218:219], off
	s_waitcnt vmcnt(8)
	s_waitcnt lgkmcnt(0)
	s_barrier
	s_waitcnt lgkmcnt(0)
	v_mfma_f32_16x16x32_bf16 v[140:143], v[108:111], v[170:173], v[140:143]
	v_mfma_f32_16x16x32_bf16 v[136:139], v[116:119], v[170:173], v[136:139]
	v_mfma_f32_16x16x32_bf16 v[132:135], v[108:111], v[178:181], v[132:135]
	v_mfma_f32_16x16x32_bf16 v[104:107], v[116:119], v[178:181], v[104:107]
	v_mfma_f32_16x16x32_bf16 v[96:99], v[108:111], v[186:189], v[96:99]
	v_mfma_f32_16x16x32_bf16 v[88:91], v[116:119], v[186:189], v[88:91]
	v_mfma_f32_16x16x32_bf16 v[80:83], v[108:111], v[194:197], v[80:83]
	v_mfma_f32_16x16x32_bf16 v[72:75], v[116:119], v[194:197], v[72:75]
	v_mfma_f32_16x16x32_bf16 v[140:143], v[112:115], v[174:177], v[140:143]
	v_mfma_f32_16x16x32_bf16 v[136:139], v[120:123], v[174:177], v[136:139]
	v_mfma_f32_16x16x32_bf16 v[132:135], v[112:115], v[182:185], v[132:135]
	v_mfma_f32_16x16x32_bf16 v[104:107], v[120:123], v[182:185], v[104:107]
	v_mfma_f32_16x16x32_bf16 v[96:99], v[112:115], v[190:193], v[96:99]
	v_mfma_f32_16x16x32_bf16 v[88:91], v[120:123], v[190:193], v[88:91]
	v_mfma_f32_16x16x32_bf16 v[80:83], v[112:115], v[204:207], v[80:83]
	v_mfma_f32_16x16x32_bf16 v[72:75], v[120:123], v[204:207], v[72:75]
	v_mfma_f32_16x16x32_bf16 v[128:131], v[146:149], v[170:173], v[128:131]
	v_mfma_f32_16x16x32_bf16 v[124:127], v[154:157], v[170:173], v[124:127]
	v_mfma_f32_16x16x32_bf16 v[100:103], v[146:149], v[178:181], v[100:103]
	v_mfma_f32_16x16x32_bf16 v[92:95], v[154:157], v[178:181], v[92:95]
	v_mfma_f32_16x16x32_bf16 v[84:87], v[146:149], v[186:189], v[84:87]
	v_mfma_f32_16x16x32_bf16 v[76:79], v[154:157], v[186:189], v[76:79]
	v_mfma_f32_16x16x32_bf16 v[68:71], v[146:149], v[194:197], v[68:71]
	v_mfma_f32_16x16x32_bf16 v[64:67], v[154:157], v[194:197], v[64:67]
	v_mfma_f32_16x16x32_bf16 v[128:131], v[150:153], v[174:177], v[128:131]
	v_mfma_f32_16x16x32_bf16 v[124:127], v[166:169], v[174:177], v[124:127]
	v_mfma_f32_16x16x32_bf16 v[100:103], v[150:153], v[182:185], v[100:103]
	v_mfma_f32_16x16x32_bf16 v[92:95], v[166:169], v[182:185], v[92:95]
	v_mfma_f32_16x16x32_bf16 v[84:87], v[150:153], v[190:193], v[84:87]
	v_mfma_f32_16x16x32_bf16 v[76:79], v[166:169], v[190:193], v[76:79]
	v_mfma_f32_16x16x32_bf16 v[68:71], v[150:153], v[204:207], v[68:71]
	v_mfma_f32_16x16x32_bf16 v[64:67], v[166:169], v[204:207], v[64:67]
	s_barrier
	s_add_i32 s48, s51, s52
	v_lshl_add_u64 v[198:199], v[198:199], 0, s[20:21]
	s_mov_b32 m0, s48
	ds_read_b128 v[170:173], v202 offset:49152
	ds_read_b128 v[174:177], v202 offset:50176
	ds_read_b128 v[178:181], v202 offset:51200
	ds_read_b128 v[182:185], v202 offset:52224
	ds_read_b128 v[186:189], v202 offset:53248
	ds_read_b128 v[190:193], v202 offset:54272
	ds_read_b128 v[194:197], v202 offset:55296
	ds_read_b128 v[204:207], v202 offset:56320
	global_load_lds_dwordx4 v[198:199], off
	v_lshl_add_u64 v[198:199], v[208:209], 0, s[20:21]
	s_add_i32 m0, s48, 0x2000
	s_add_i32 s48, s74, s52
	global_load_lds_dwordx4 v[198:199], off
	v_lshl_add_u64 v[198:199], v[210:211], 0, s[20:21]
	s_mov_b32 m0, s48
	s_nop 0
	global_load_lds_dwordx4 v[198:199], off
	v_lshl_add_u64 v[198:199], v[212:213], 0, s[20:21]
	s_add_i32 m0, s48, 0x2000
	s_nop 0
	global_load_lds_dwordx4 v[198:199], off
	v_lshl_add_u64 v[198:199], v[214:215], 0, s[20:21]
	s_mov_b32 m0, s62
	s_nop 0
	global_load_lds_dwordx4 v[198:199], off
	v_lshl_add_u64 v[198:199], v[216:217], 0, s[20:21]
	s_mov_b32 m0, s63
	s_nop 0
	global_load_lds_dwordx4 v[198:199], off
	s_waitcnt vmcnt(8)
	s_waitcnt lgkmcnt(0)
	s_barrier
	s_waitcnt lgkmcnt(0)
	v_mfma_f32_16x16x32_bf16 v[60:63], v[108:111], v[170:173], v[60:63]
	v_mfma_f32_16x16x32_bf16 v[56:59], v[116:119], v[170:173], v[56:59]
	v_mfma_f32_16x16x32_bf16 v[48:51], v[108:111], v[178:181], v[48:51]
	v_mfma_f32_16x16x32_bf16 v[40:43], v[116:119], v[178:181], v[40:43]
	v_mfma_f32_16x16x32_bf16 v[32:35], v[108:111], v[186:189], v[32:35]
	v_mfma_f32_16x16x32_bf16 v[24:27], v[116:119], v[186:189], v[24:27]
	v_mfma_f32_16x16x32_bf16 v[16:19], v[108:111], v[194:197], v[16:19]
	v_mfma_f32_16x16x32_bf16 v[8:11], v[116:119], v[194:197], v[8:11]
	v_mfma_f32_16x16x32_bf16 v[60:63], v[112:115], v[174:177], v[60:63]
	v_mfma_f32_16x16x32_bf16 v[56:59], v[120:123], v[174:177], v[56:59]
	v_mfma_f32_16x16x32_bf16 v[48:51], v[112:115], v[182:185], v[48:51]
	v_mfma_f32_16x16x32_bf16 v[40:43], v[120:123], v[182:185], v[40:43]
	v_mfma_f32_16x16x32_bf16 v[32:35], v[112:115], v[190:193], v[32:35]
	v_mfma_f32_16x16x32_bf16 v[24:27], v[120:123], v[190:193], v[24:27]
	v_mfma_f32_16x16x32_bf16 v[16:19], v[112:115], v[204:207], v[16:19]
	v_mfma_f32_16x16x32_bf16 v[8:11], v[120:123], v[204:207], v[8:11]
	v_mfma_f32_16x16x32_bf16 v[52:55], v[146:149], v[170:173], v[52:55]
	v_mfma_f32_16x16x32_bf16 v[44:47], v[154:157], v[170:173], v[44:47]
	v_mfma_f32_16x16x32_bf16 v[36:39], v[146:149], v[178:181], v[36:39]
	v_mfma_f32_16x16x32_bf16 v[28:31], v[154:157], v[178:181], v[28:31]
	v_mfma_f32_16x16x32_bf16 v[20:23], v[146:149], v[186:189], v[20:23]
	v_mfma_f32_16x16x32_bf16 v[12:15], v[154:157], v[186:189], v[12:15]
	v_mfma_f32_16x16x32_bf16 v[4:7], v[146:149], v[194:197], v[4:7]
	v_mfma_f32_16x16x32_bf16 v[0:3], v[154:157], v[194:197], v[0:3]
	v_mfma_f32_16x16x32_bf16 v[52:55], v[150:153], v[174:177], v[52:55]
	v_mfma_f32_16x16x32_bf16 v[44:47], v[166:169], v[174:177], v[44:47]
	v_mfma_f32_16x16x32_bf16 v[36:39], v[150:153], v[182:185], v[36:39]
	v_mfma_f32_16x16x32_bf16 v[28:31], v[166:169], v[182:185], v[28:31]
	v_mfma_f32_16x16x32_bf16 v[20:23], v[150:153], v[190:193], v[20:23]
	v_mfma_f32_16x16x32_bf16 v[12:15], v[166:169], v[190:193], v[12:15]
	v_mfma_f32_16x16x32_bf16 v[4:7], v[150:153], v[204:207], v[4:7]
	v_mfma_f32_16x16x32_bf16 v[0:3], v[166:169], v[204:207], v[0:3]
	s_barrier
	s_add_u32 s40, s40, 0x100
	s_addc_u32 s41, s41, 0
	s_add_u32 s4, s4, 0x100
	s_addc_u32 s5, s5, 0
	s_cmp_ge_u32 s50, s59
	s_mov_b32 s48, s50
	s_cbranch_scc0 .LBB0_437
	s_and_b64 vcc, exec, s[24:25]
	s_cbranch_vccz .LBB0_440
	s_barrier

.LBB0_486:
	s_add_u32 s42, s40, 0xfffc0080
	s_addc_u32 s43, s41, -1
	s_add_i32 s79, 0, 0x10000
	s_cmp_eq_u32 s78, 12
	s_cselect_b32 s53, s4, s43
	s_cselect_b32 s52, s5, s42
	v_add_u32_e32 v144, s79, v172
	s_cselect_b32 s43, s27, s47
	s_cselect_b32 s42, s39, s45
	s_add_i32 s82, 0, 0x14000
	ds_read_b128 v[128:131], v144
	ds_read_b128 v[146:149], v144 offset:1024
	ds_read_b128 v[150:153], v144 offset:2048
	ds_read_b128 v[154:157], v144 offset:3072
	v_add_u32_e32 v144, s82, v172
	ds_read_b128 v[160:163], v144
	ds_read_b128 v[164:167], v144 offset:1024
	ds_read_b128 v[174:177], v144 offset:2048
	ds_read_b128 v[178:181], v144 offset:3072
	v_lshl_add_u64 v[168:169], s[40:41], 0, v[140:141]
	s_add_i32 m0, s58, 0xc000
	ds_read_b128 v[182:185], v173
	ds_read_b128 v[186:189], v173 offset:1024
	ds_read_b128 v[190:193], v173 offset:2048
	ds_read_b128 v[194:197], v173 offset:3072
	ds_read_b128 v[198:201], v173 offset:4096
	ds_read_b128 v[202:205], v173 offset:5120
	ds_read_b128 v[206:209], v173 offset:6144
	ds_read_b128 v[210:213], v173 offset:7168
	global_load_lds_dwordx4 v[168:169], off
	v_lshl_add_u64 v[168:169], s[40:41], 0, v[142:143]
	s_add_i32 m0, s58, 0xe000
	s_nop 0
	global_load_lds_dwordx4 v[168:169], off
	s_waitcnt vmcnt(8)
	s_waitcnt lgkmcnt(0)
	s_barrier
	s_waitcnt lgkmcnt(0)
	v_mfma_f32_16x16x32_bf16 v[124:127], v[128:131], v[182:185], v[124:127]
	v_mfma_f32_16x16x32_bf16 v[120:123], v[150:153], v[182:185], v[120:123]
	v_mfma_f32_16x16x32_bf16 v[108:111], v[128:131], v[190:193], v[108:111]
	v_mfma_f32_16x16x32_bf16 v[104:107], v[150:153], v[190:193], v[104:107]
	v_mfma_f32_16x16x32_bf16 v[92:95], v[128:131], v[198:201], v[92:95]
	v_mfma_f32_16x16x32_bf16 v[88:91], v[150:153], v[198:201], v[88:91]
	v_mfma_f32_16x16x32_bf16 v[76:79], v[128:131], v[206:209], v[76:79]
	v_mfma_f32_16x16x32_bf16 v[72:75], v[150:153], v[206:209], v[72:75]
	v_mfma_f32_16x16x32_bf16 v[124:127], v[146:149], v[186:189], v[124:127]
	v_mfma_f32_16x16x32_bf16 v[120:123], v[154:157], v[186:189], v[120:123]
	v_mfma_f32_16x16x32_bf16 v[108:111], v[146:149], v[194:197], v[108:111]
	v_mfma_f32_16x16x32_bf16 v[104:107], v[154:157], v[194:197], v[104:107]
	v_mfma_f32_16x16x32_bf16 v[92:95], v[146:149], v[202:205], v[92:95]
	v_mfma_f32_16x16x32_bf16 v[88:91], v[154:157], v[202:205], v[88:91]
	v_mfma_f32_16x16x32_bf16 v[76:79], v[146:149], v[210:213], v[76:79]
	v_mfma_f32_16x16x32_bf16 v[72:75], v[154:157], v[210:213], v[72:75]
	v_mfma_f32_16x16x32_bf16 v[116:119], v[160:163], v[182:185], v[116:119]
	v_mfma_f32_16x16x32_bf16 v[112:115], v[174:177], v[182:185], v[112:115]
	v_mfma_f32_16x16x32_bf16 v[100:103], v[160:163], v[190:193], v[100:103]
	v_mfma_f32_16x16x32_bf16 v[96:99], v[174:177], v[190:193], v[96:99]
	v_mfma_f32_16x16x32_bf16 v[84:87], v[160:163], v[198:201], v[84:87]
	v_mfma_f32_16x16x32_bf16 v[80:83], v[174:177], v[198:201], v[80:83]
	v_mfma_f32_16x16x32_bf16 v[68:71], v[160:163], v[206:209], v[68:71]
	v_mfma_f32_16x16x32_bf16 v[64:67], v[174:177], v[206:209], v[64:67]
	v_mfma_f32_16x16x32_bf16 v[116:119], v[164:167], v[186:189], v[116:119]
	v_mfma_f32_16x16x32_bf16 v[112:115], v[178:181], v[186:189], v[112:115]
	v_mfma_f32_16x16x32_bf16 v[100:103], v[164:167], v[194:197], v[100:103]
	v_mfma_f32_16x16x32_bf16 v[96:99], v[178:181], v[194:197], v[96:99]
	v_mfma_f32_16x16x32_bf16 v[84:87], v[164:167], v[202:205], v[84:87]
	v_mfma_f32_16x16x32_bf16 v[80:83], v[178:181], v[202:205], v[80:83]
	v_mfma_f32_16x16x32_bf16 v[68:71], v[164:167], v[210:213], v[68:71]
	v_mfma_f32_16x16x32_bf16 v[64:67], v[178:181], v[210:213], v[64:67]
	s_barrier
	s_add_i32 s79, s79, s57
	v_lshl_add_u64 v[168:169], s[42:43], 0, v[134:135]
	s_mov_b32 m0, s79
	ds_read_b128 v[182:185], v173 offset:16384
	ds_read_b128 v[186:189], v173 offset:17408
	ds_read_b128 v[190:193], v173 offset:18432
	ds_read_b128 v[194:197], v173 offset:19456
	ds_read_b128 v[198:201], v173 offset:20480
	ds_read_b128 v[202:205], v173 offset:21504
	ds_read_b128 v[206:209], v173 offset:22528
	ds_read_b128 v[210:213], v173 offset:23552
	global_load_lds_dwordx4 v[168:169], off
	s_add_i32 m0, s79, 0x2000
	s_add_u32 s80, s42, 0x40000
	v_lshl_add_u64 v[214:215], s[42:43], 0, v[138:139]
	s_addc_u32 s81, s43, 0
	s_add_i32 s79, s82, s57
	global_load_lds_dwordx4 v[214:215], off
	v_lshl_add_u64 v[216:217], s[80:81], 0, v[134:135]
	s_mov_b32 m0, s79
	v_lshl_add_u64 v[218:219], s[52:53], 0, v[136:137]
	global_load_lds_dwordx4 v[216:217], off
	v_lshl_add_u64 v[216:217], s[80:81], 0, v[138:139]
	s_add_i32 m0, s79, 0x2000
	s_nop 0
	global_load_lds_dwordx4 v[216:217], off
	v_lshl_add_u64 v[216:217], s[52:53], 0, v[132:133]
	s_mov_b32 m0, s58
	s_nop 0
	global_load_lds_dwordx4 v[216:217], off
	s_mov_b32 m0, s59
	s_nop 0
	global_load_lds_dwordx4 v[218:219], off
	s_waitcnt vmcnt(8)
	s_waitcnt lgkmcnt(0)
	s_barrier
	s_waitcnt lgkmcnt(0)
	v_mfma_f32_16x16x32_bf16 v[60:63], v[128:131], v[182:185], v[60:63]
	v_mfma_f32_16x16x32_bf16 v[56:59], v[150:153], v[182:185], v[56:59]
	v_mfma_f32_16x16x32_bf16 v[44:47], v[128:131], v[190:193], v[44:47]
	v_mfma_f32_16x16x32_bf16 v[40:43], v[150:153], v[190:193], v[40:43]
	v_mfma_f32_16x16x32_bf16 v[28:31], v[128:131], v[198:201], v[28:31]
	v_mfma_f32_16x16x32_bf16 v[24:27], v[150:153], v[198:201], v[24:27]
	v_mfma_f32_16x16x32_bf16 v[12:15], v[128:131], v[206:209], v[12:15]
	v_mfma_f32_16x16x32_bf16 v[8:11], v[150:153], v[206:209], v[8:11]
	v_mfma_f32_16x16x32_bf16 v[60:63], v[146:149], v[186:189], v[60:63]
	v_mfma_f32_16x16x32_bf16 v[56:59], v[154:157], v[186:189], v[56:59]
	v_mfma_f32_16x16x32_bf16 v[44:47], v[146:149], v[194:197], v[44:47]
	v_mfma_f32_16x16x32_bf16 v[40:43], v[154:157], v[194:197], v[40:43]
	v_mfma_f32_16x16x32_bf16 v[28:31], v[146:149], v[202:205], v[28:31]
	v_mfma_f32_16x16x32_bf16 v[24:27], v[154:157], v[202:205], v[24:27]
	v_mfma_f32_16x16x32_bf16 v[12:15], v[146:149], v[210:213], v[12:15]
	v_mfma_f32_16x16x32_bf16 v[8:11], v[154:157], v[210:213], v[8:11]
	v_mfma_f32_16x16x32_bf16 v[52:55], v[160:163], v[182:185], v[52:55]
	v_mfma_f32_16x16x32_bf16 v[48:51], v[174:177], v[182:185], v[48:51]
	v_mfma_f32_16x16x32_bf16 v[36:39], v[160:163], v[190:193], v[36:39]
	v_mfma_f32_16x16x32_bf16 v[32:35], v[174:177], v[190:193], v[32:35]
	v_mfma_f32_16x16x32_bf16 v[20:23], v[160:163], v[198:201], v[20:23]
	v_mfma_f32_16x16x32_bf16 v[16:19], v[174:177], v[198:201], v[16:19]
	v_mfma_f32_16x16x32_bf16 v[4:7], v[160:163], v[206:209], v[4:7]
	v_mfma_f32_16x16x32_bf16 v[0:3], v[174:177], v[206:209], v[0:3]
	v_mfma_f32_16x16x32_bf16 v[52:55], v[164:167], v[186:189], v[52:55]
	v_mfma_f32_16x16x32_bf16 v[48:51], v[178:181], v[186:189], v[48:51]
	v_mfma_f32_16x16x32_bf16 v[36:39], v[164:167], v[194:197], v[36:39]
	v_mfma_f32_16x16x32_bf16 v[32:35], v[178:181], v[194:197], v[32:35]
	v_mfma_f32_16x16x32_bf16 v[20:23], v[164:167], v[202:205], v[20:23]
	v_mfma_f32_16x16x32_bf16 v[16:19], v[178:181], v[202:205], v[16:19]
	v_mfma_f32_16x16x32_bf16 v[4:7], v[164:167], v[210:213], v[4:7]
	v_mfma_f32_16x16x32_bf16 v[0:3], v[178:181], v[210:213], v[0:3]
	s_barrier
	s_add_i32 s79, 0, 0x18000
	v_add_u32_e32 v144, s79, v172
	s_add_i32 s80, 0, 0x1c000
	ds_read_b128 v[128:131], v144
	ds_read_b128 v[146:149], v144 offset:1024
	ds_read_b128 v[150:153], v144 offset:2048
	ds_read_b128 v[154:157], v144 offset:3072
	v_add_u32_e32 v144, s80, v172
	ds_read_b128 v[160:163], v144
	ds_read_b128 v[164:167], v144 offset:1024
	ds_read_b128 v[174:177], v144 offset:2048
	ds_read_b128 v[178:181], v144 offset:3072
	s_add_u32 s52, s52, 0x40000
	s_addc_u32 s53, s53, 0
	s_mov_b32 m0, s60
	v_lshl_add_u64 v[220:221], s[52:53], 0, v[132:133]
	ds_read_b128 v[182:185], v173 offset:32768
	ds_read_b128 v[186:189], v173 offset:33792
	ds_read_b128 v[190:193], v173 offset:34816
	ds_read_b128 v[194:197], v173 offset:35840
	ds_read_b128 v[198:201], v173 offset:36864
	ds_read_b128 v[202:205], v173 offset:37888
	ds_read_b128 v[206:209], v173 offset:38912
	ds_read_b128 v[210:213], v173 offset:39936
	global_load_lds_dwordx4 v[220:221], off
	v_lshl_add_u64 v[220:221], s[52:53], 0, v[136:137]
	s_mov_b32 m0, s61
	s_nop 0
	global_load_lds_dwordx4 v[220:221], off
	s_waitcnt vmcnt(8)
	s_waitcnt lgkmcnt(0)
	s_barrier
	s_waitcnt lgkmcnt(0)
	v_mfma_f32_16x16x32_bf16 v[124:127], v[128:131], v[182:185], v[124:127]
	v_mfma_f32_16x16x32_bf16 v[120:123], v[150:153], v[182:185], v[120:123]
	v_mfma_f32_16x16x32_bf16 v[108:111], v[128:131], v[190:193], v[108:111]
	v_mfma_f32_16x16x32_bf16 v[104:107], v[150:153], v[190:193], v[104:107]
	v_mfma_f32_16x16x32_bf16 v[92:95], v[128:131], v[198:201], v[92:95]
	v_mfma_f32_16x16x32_bf16 v[88:91], v[150:153], v[198:201], v[88:91]
	v_mfma_f32_16x16x32_bf16 v[76:79], v[128:131], v[206:209], v[76:79]
	v_mfma_f32_16x16x32_bf16 v[72:75], v[150:153], v[206:209], v[72:75]
	v_mfma_f32_16x16x32_bf16 v[124:127], v[146:149], v[186:189], v[124:127]
	v_mfma_f32_16x16x32_bf16 v[120:123], v[154:157], v[186:189], v[120:123]
	v_mfma_f32_16x16x32_bf16 v[108:111], v[146:149], v[194:197], v[108:111]
	v_mfma_f32_16x16x32_bf16 v[104:107], v[154:157], v[194:197], v[104:107]
	v_mfma_f32_16x16x32_bf16 v[92:95], v[146:149], v[202:205], v[92:95]
	v_mfma_f32_16x16x32_bf16 v[88:91], v[154:157], v[202:205], v[88:91]
	v_mfma_f32_16x16x32_bf16 v[76:79], v[146:149], v[210:213], v[76:79]
	v_mfma_f32_16x16x32_bf16 v[72:75], v[154:157], v[210:213], v[72:75]
	v_mfma_f32_16x16x32_bf16 v[116:119], v[160:163], v[182:185], v[116:119]
	v_mfma_f32_16x16x32_bf16 v[112:115], v[174:177], v[182:185], v[112:115]
	v_mfma_f32_16x16x32_bf16 v[100:103], v[160:163], v[190:193], v[100:103]
	v_mfma_f32_16x16x32_bf16 v[96:99], v[174:177], v[190:193], v[96:99]
	v_mfma_f32_16x16x32_bf16 v[84:87], v[160:163], v[198:201], v[84:87]
	v_mfma_f32_16x16x32_bf16 v[80:83], v[174:177], v[198:201], v[80:83]
	v_mfma_f32_16x16x32_bf16 v[68:71], v[160:163], v[206:209], v[68:71]
	v_mfma_f32_16x16x32_bf16 v[64:67], v[174:177], v[206:209], v[64:67]
	v_mfma_f32_16x16x32_bf16 v[116:119], v[164:167], v[186:189], v[116:119]
	v_mfma_f32_16x16x32_bf16 v[112:115], v[178:181], v[186:189], v[112:115]
	v_mfma_f32_16x16x32_bf16 v[100:103], v[164:167], v[194:197], v[100:103]
	v_mfma_f32_16x16x32_bf16 v[96:99], v[178:181], v[194:197], v[96:99]
	v_mfma_f32_16x16x32_bf16 v[84:87], v[164:167], v[202:205], v[84:87]
	v_mfma_f32_16x16x32_bf16 v[80:83], v[178:181], v[202:205], v[80:83]
	v_mfma_f32_16x16x32_bf16 v[68:71], v[164:167], v[210:213], v[68:71]
	v_mfma_f32_16x16x32_bf16 v[64:67], v[178:181], v[210:213], v[64:67]
	s_barrier
	s_add_i32 s52, s79, s57
	v_lshl_add_u64 v[168:169], v[168:169], 0, s[20:21]
	s_mov_b32 m0, s52
	ds_read_b128 v[182:185], v173 offset:49152
	ds_read_b128 v[186:189], v173 offset:50176
	ds_read_b128 v[190:193], v173 offset:51200
	ds_read_b128 v[194:197], v173 offset:52224
	ds_read_b128 v[198:201], v173 offset:53248
	ds_read_b128 v[202:205], v173 offset:54272
	ds_read_b128 v[206:209], v173 offset:55296
	ds_read_b128 v[210:213], v173 offset:56320
	global_load_lds_dwordx4 v[168:169], off
	s_add_i32 m0, s52, 0x2000
	s_add_u32 s42, s42, 0x40080
	v_lshl_add_u64 v[168:169], v[214:215], 0, s[20:21]
	s_addc_u32 s43, s43, 0
	s_add_i32 s52, s80, s57
	global_load_lds_dwordx4 v[168:169], off
	v_lshl_add_u64 v[168:169], s[42:43], 0, v[134:135]
	s_mov_b32 m0, s52
	s_nop 0
	global_load_lds_dwordx4 v[168:169], off
	v_lshl_add_u64 v[168:169], s[42:43], 0, v[138:139]
	s_add_i32 m0, s52, 0x2000
	s_nop 0
	global_load_lds_dwordx4 v[168:169], off
	v_lshl_add_u64 v[168:169], v[216:217], 0, s[20:21]
	s_mov_b32 m0, s64
	s_nop 0
	global_load_lds_dwordx4 v[168:169], off
	v_lshl_add_u64 v[168:169], v[218:219], 0, s[20:21]
	s_mov_b32 m0, s65
	s_nop 0
	global_load_lds_dwordx4 v[168:169], off
	s_waitcnt vmcnt(8)
	s_waitcnt lgkmcnt(0)
	s_barrier
	s_waitcnt lgkmcnt(0)
	v_mfma_f32_16x16x32_bf16 v[60:63], v[128:131], v[182:185], v[60:63]
	v_mfma_f32_16x16x32_bf16 v[56:59], v[150:153], v[182:185], v[56:59]
	v_mfma_f32_16x16x32_bf16 v[44:47], v[128:131], v[190:193], v[44:47]
	v_mfma_f32_16x16x32_bf16 v[40:43], v[150:153], v[190:193], v[40:43]
	v_mfma_f32_16x16x32_bf16 v[28:31], v[128:131], v[198:201], v[28:31]
	v_mfma_f32_16x16x32_bf16 v[24:27], v[150:153], v[198:201], v[24:27]
	v_mfma_f32_16x16x32_bf16 v[12:15], v[128:131], v[206:209], v[12:15]
	v_mfma_f32_16x16x32_bf16 v[8:11], v[150:153], v[206:209], v[8:11]
	v_mfma_f32_16x16x32_bf16 v[60:63], v[146:149], v[186:189], v[60:63]
	v_mfma_f32_16x16x32_bf16 v[56:59], v[154:157], v[186:189], v[56:59]
	v_mfma_f32_16x16x32_bf16 v[44:47], v[146:149], v[194:197], v[44:47]
	v_mfma_f32_16x16x32_bf16 v[40:43], v[154:157], v[194:197], v[40:43]
	v_mfma_f32_16x16x32_bf16 v[28:31], v[146:149], v[202:205], v[28:31]
	v_mfma_f32_16x16x32_bf16 v[24:27], v[154:157], v[202:205], v[24:27]
	v_mfma_f32_16x16x32_bf16 v[12:15], v[146:149], v[210:213], v[12:15]
	v_mfma_f32_16x16x32_bf16 v[8:11], v[154:157], v[210:213], v[8:11]
	v_mfma_f32_16x16x32_bf16 v[52:55], v[160:163], v[182:185], v[52:55]
	v_mfma_f32_16x16x32_bf16 v[48:51], v[174:177], v[182:185], v[48:51]
	v_mfma_f32_16x16x32_bf16 v[36:39], v[160:163], v[190:193], v[36:39]
	v_mfma_f32_16x16x32_bf16 v[32:35], v[174:177], v[190:193], v[32:35]
	v_mfma_f32_16x16x32_bf16 v[20:23], v[160:163], v[198:201], v[20:23]
	v_mfma_f32_16x16x32_bf16 v[16:19], v[174:177], v[198:201], v[16:19]
	v_mfma_f32_16x16x32_bf16 v[4:7], v[160:163], v[206:209], v[4:7]
	v_mfma_f32_16x16x32_bf16 v[0:3], v[174:177], v[206:209], v[0:3]
	v_mfma_f32_16x16x32_bf16 v[52:55], v[164:167], v[186:189], v[52:55]
	v_mfma_f32_16x16x32_bf16 v[48:51], v[178:181], v[186:189], v[48:51]
	v_mfma_f32_16x16x32_bf16 v[36:39], v[164:167], v[194:197], v[36:39]
	v_mfma_f32_16x16x32_bf16 v[32:35], v[178:181], v[194:197], v[32:35]
	v_mfma_f32_16x16x32_bf16 v[20:23], v[164:167], v[202:205], v[20:23]
	v_mfma_f32_16x16x32_bf16 v[16:19], v[178:181], v[202:205], v[16:19]
	v_mfma_f32_16x16x32_bf16 v[4:7], v[164:167], v[210:213], v[4:7]
	v_mfma_f32_16x16x32_bf16 v[0:3], v[178:181], v[210:213], v[0:3]
	s_barrier
	s_add_i32 s78, s78, 2
	s_add_u32 s40, s40, 0x100
	s_addc_u32 s41, s41, 0
	s_add_u32 s45, s45, 0x100
	s_addc_u32 s47, s47, 0
	s_cmp_gt_u32 s78, 13
	s_cbranch_scc0 .LBB0_486
	s_and_b64 vcc, exec, s[24:25]
	s_cbranch_vccz .LBB0_489
	s_barrier

.LBB0_625:
	s_add_u32 s50, s40, 0xfffc0080
	s_addc_u32 s51, s41, -1
	s_add_i32 s70, 0, 0x10000
	s_cmp_eq_u32 s69, 12
	s_cselect_b32 s53, s4, s51
	s_cselect_b32 s52, s5, s50
	s_cselect_b32 s51, s39, s68
	s_cselect_b32 s50, s43, s45
	s_add_i32 s72, 0, 0x14000
	v_add_u32_e32 v44, s70, v177
	v_add_u32_e32 v170, s72, v177
	ds_read_b128 v[32:35], v44
	ds_read_b128 v[36:39], v44 offset:1024
	ds_read_b128 v[40:43], v44 offset:2048
	ds_read_b128 v[44:47], v44 offset:3072
	ds_read_b128 v[146:149], v170
	ds_read_b128 v[150:153], v170 offset:1024
	ds_read_b128 v[154:157], v170 offset:2048
	ds_read_b128 v[170:173], v170 offset:3072
	v_lshl_add_u64 v[174:175], s[40:41], 0, v[166:167]
	s_add_i32 m0, s54, 0xc000
	ds_read_b128 v[180:183], v178
	ds_read_b128 v[184:187], v178 offset:1024
	ds_read_b128 v[188:191], v178 offset:2048
	ds_read_b128 v[192:195], v178 offset:3072
	ds_read_b128 v[196:199], v178 offset:4096
	ds_read_b128 v[200:203], v178 offset:5120
	ds_read_b128 v[204:207], v178 offset:6144
	ds_read_b128 v[208:211], v178 offset:7168
	global_load_lds_dwordx4 v[174:175], off
	v_lshl_add_u64 v[174:175], s[40:41], 0, v[168:169]
	s_add_i32 m0, s54, 0xe000
	s_nop 0
	global_load_lds_dwordx4 v[174:175], off
	s_waitcnt vmcnt(8)
	s_waitcnt lgkmcnt(0)
	s_barrier
	s_waitcnt lgkmcnt(0)
	v_mfma_f32_16x16x32_bf16 v[140:143], v[32:35], v[180:183], v[140:143]
	v_mfma_f32_16x16x32_bf16 v[136:139], v[40:43], v[180:183], v[136:139]
	v_mfma_f32_16x16x32_bf16 v[124:127], v[32:35], v[188:191], v[124:127]
	v_mfma_f32_16x16x32_bf16 v[120:123], v[40:43], v[188:191], v[120:123]
	v_mfma_f32_16x16x32_bf16 v[108:111], v[32:35], v[196:199], v[108:111]
	v_mfma_f32_16x16x32_bf16 v[104:107], v[40:43], v[196:199], v[104:107]
	v_mfma_f32_16x16x32_bf16 v[92:95], v[32:35], v[204:207], v[92:95]
	v_mfma_f32_16x16x32_bf16 v[88:91], v[40:43], v[204:207], v[88:91]
	v_mfma_f32_16x16x32_bf16 v[140:143], v[36:39], v[184:187], v[140:143]
	v_mfma_f32_16x16x32_bf16 v[136:139], v[44:47], v[184:187], v[136:139]
	v_mfma_f32_16x16x32_bf16 v[124:127], v[36:39], v[192:195], v[124:127]
	v_mfma_f32_16x16x32_bf16 v[120:123], v[44:47], v[192:195], v[120:123]
	v_mfma_f32_16x16x32_bf16 v[108:111], v[36:39], v[200:203], v[108:111]
	v_mfma_f32_16x16x32_bf16 v[104:107], v[44:47], v[200:203], v[104:107]
	v_mfma_f32_16x16x32_bf16 v[92:95], v[36:39], v[208:211], v[92:95]
	v_mfma_f32_16x16x32_bf16 v[88:91], v[44:47], v[208:211], v[88:91]
	v_mfma_f32_16x16x32_bf16 v[132:135], v[146:149], v[180:183], v[132:135]
	v_mfma_f32_16x16x32_bf16 v[128:131], v[154:157], v[180:183], v[128:131]
	v_mfma_f32_16x16x32_bf16 v[116:119], v[146:149], v[188:191], v[116:119]
	v_mfma_f32_16x16x32_bf16 v[112:115], v[154:157], v[188:191], v[112:115]
	v_mfma_f32_16x16x32_bf16 v[100:103], v[146:149], v[196:199], v[100:103]
	v_mfma_f32_16x16x32_bf16 v[96:99], v[154:157], v[196:199], v[96:99]
	v_mfma_f32_16x16x32_bf16 v[84:87], v[146:149], v[204:207], v[84:87]
	v_mfma_f32_16x16x32_bf16 v[80:83], v[154:157], v[204:207], v[80:83]
	v_mfma_f32_16x16x32_bf16 v[132:135], v[150:153], v[184:187], v[132:135]
	v_mfma_f32_16x16x32_bf16 v[128:131], v[170:173], v[184:187], v[128:131]
	v_mfma_f32_16x16x32_bf16 v[116:119], v[150:153], v[192:195], v[116:119]
	v_mfma_f32_16x16x32_bf16 v[112:115], v[170:173], v[192:195], v[112:115]
	v_mfma_f32_16x16x32_bf16 v[100:103], v[150:153], v[200:203], v[100:103]
	v_mfma_f32_16x16x32_bf16 v[96:99], v[170:173], v[200:203], v[96:99]
	v_mfma_f32_16x16x32_bf16 v[84:87], v[150:153], v[208:211], v[84:87]
	v_mfma_f32_16x16x32_bf16 v[80:83], v[170:173], v[208:211], v[80:83]
	s_barrier
	s_add_i32 s70, s70, s27
	v_lshl_add_u64 v[174:175], s[50:51], 0, v[144:145]
	s_mov_b32 m0, s70
	ds_read_b128 v[180:183], v178 offset:16384
	ds_read_b128 v[184:187], v178 offset:17408
	ds_read_b128 v[188:191], v178 offset:18432
	ds_read_b128 v[192:195], v178 offset:19456
	ds_read_b128 v[196:199], v178 offset:20480
	ds_read_b128 v[200:203], v178 offset:21504
	ds_read_b128 v[204:207], v178 offset:22528
	ds_read_b128 v[208:211], v178 offset:23552
	global_load_lds_dwordx4 v[174:175], off
	s_add_i32 m0, s70, 0x2000
	s_add_u32 s70, s50, 0x40000
	v_lshl_add_u64 v[212:213], s[50:51], 0, v[164:165]
	s_addc_u32 s71, s51, 0
	s_add_i32 s72, s72, s27
	global_load_lds_dwordx4 v[212:213], off
	v_lshl_add_u64 v[214:215], s[70:71], 0, v[144:145]
	s_mov_b32 m0, s72
	v_lshl_add_u64 v[216:217], s[52:53], 0, v[162:163]
	global_load_lds_dwordx4 v[214:215], off
	v_lshl_add_u64 v[214:215], s[70:71], 0, v[164:165]
	s_add_i32 m0, s72, 0x2000
	s_nop 0
	global_load_lds_dwordx4 v[214:215], off
	v_lshl_add_u64 v[214:215], s[52:53], 0, v[160:161]
	s_mov_b32 m0, s54
	s_nop 0
	global_load_lds_dwordx4 v[214:215], off
	s_mov_b32 m0, s55
	s_nop 0
	global_load_lds_dwordx4 v[216:217], off
	s_waitcnt vmcnt(8)
	s_waitcnt lgkmcnt(0)
	s_barrier
	s_waitcnt lgkmcnt(0)
	v_mfma_f32_16x16x32_bf16 v[76:79], v[32:35], v[180:183], v[76:79]
	v_mfma_f32_16x16x32_bf16 v[72:75], v[40:43], v[180:183], v[72:75]
	v_mfma_f32_16x16x32_bf16 v[60:63], v[32:35], v[188:191], v[60:63]
	v_mfma_f32_16x16x32_bf16 v[56:59], v[40:43], v[188:191], v[56:59]
	v_mfma_f32_16x16x32_bf16 v[28:31], v[32:35], v[196:199], v[28:31]
	v_mfma_f32_16x16x32_bf16 v[24:27], v[40:43], v[196:199], v[24:27]
	v_mfma_f32_16x16x32_bf16 v[12:15], v[32:35], v[204:207], v[12:15]
	v_mfma_f32_16x16x32_bf16 v[8:11], v[40:43], v[204:207], v[8:11]
	v_mfma_f32_16x16x32_bf16 v[76:79], v[36:39], v[184:187], v[76:79]
	v_mfma_f32_16x16x32_bf16 v[72:75], v[44:47], v[184:187], v[72:75]
	v_mfma_f32_16x16x32_bf16 v[60:63], v[36:39], v[192:195], v[60:63]
	v_mfma_f32_16x16x32_bf16 v[56:59], v[44:47], v[192:195], v[56:59]
	v_mfma_f32_16x16x32_bf16 v[28:31], v[36:39], v[200:203], v[28:31]
	v_mfma_f32_16x16x32_bf16 v[24:27], v[44:47], v[200:203], v[24:27]
	v_mfma_f32_16x16x32_bf16 v[12:15], v[36:39], v[208:211], v[12:15]
	v_mfma_f32_16x16x32_bf16 v[8:11], v[44:47], v[208:211], v[8:11]
	v_mfma_f32_16x16x32_bf16 v[20:23], v[146:149], v[196:199], v[20:23]
	v_mfma_f32_16x16x32_bf16 v[16:19], v[154:157], v[196:199], v[16:19]
	v_mfma_f32_16x16x32_bf16 v[4:7], v[146:149], v[204:207], v[4:7]
	v_mfma_f32_16x16x32_bf16 v[0:3], v[154:157], v[204:207], v[0:3]
	v_mfma_f32_16x16x32_bf16 v[32:35], v[146:149], v[180:183], v[68:71]
	v_mfma_f32_16x16x32_bf16 v[36:39], v[154:157], v[180:183], v[64:67]
	v_mfma_f32_16x16x32_bf16 v[40:43], v[146:149], v[188:191], v[52:55]
	v_mfma_f32_16x16x32_bf16 v[44:47], v[154:157], v[188:191], v[48:51]
	v_mfma_f32_16x16x32_bf16 v[20:23], v[150:153], v[200:203], v[20:23]
	v_mfma_f32_16x16x32_bf16 v[16:19], v[170:173], v[200:203], v[16:19]
	v_mfma_f32_16x16x32_bf16 v[4:7], v[150:153], v[208:211], v[4:7]
	v_mfma_f32_16x16x32_bf16 v[0:3], v[170:173], v[208:211], v[0:3]
	v_mfma_f32_16x16x32_bf16 v[32:35], v[150:153], v[184:187], v[32:35]
	v_mfma_f32_16x16x32_bf16 v[36:39], v[170:173], v[184:187], v[36:39]
	v_mfma_f32_16x16x32_bf16 v[40:43], v[150:153], v[192:195], v[40:43]
	v_mfma_f32_16x16x32_bf16 v[44:47], v[170:173], v[192:195], v[44:47]
	s_barrier
	s_add_i32 s70, 0, 0x18000
	s_add_i32 s71, 0, 0x1c000
	v_add_u32_e32 v68, s70, v177
	v_add_u32_e32 v170, s71, v177
	ds_read_b128 v[48:51], v68
	ds_read_b128 v[52:55], v68 offset:1024
	ds_read_b128 v[64:67], v68 offset:2048
	ds_read_b128 v[68:71], v68 offset:3072
	ds_read_b128 v[146:149], v170
	ds_read_b128 v[150:153], v170 offset:1024
	ds_read_b128 v[154:157], v170 offset:2048
	ds_read_b128 v[170:173], v170 offset:3072
	s_add_u32 s52, s52, 0x40000
	s_addc_u32 s53, s53, 0
	s_mov_b32 m0, s56
	v_lshl_add_u64 v[218:219], s[52:53], 0, v[160:161]
	ds_read_b128 v[180:183], v178 offset:32768
	ds_read_b128 v[184:187], v178 offset:33792
	ds_read_b128 v[188:191], v178 offset:34816
	ds_read_b128 v[192:195], v178 offset:35840
	ds_read_b128 v[196:199], v178 offset:36864
	ds_read_b128 v[200:203], v178 offset:37888
	ds_read_b128 v[204:207], v178 offset:38912
	ds_read_b128 v[208:211], v178 offset:39936
	global_load_lds_dwordx4 v[218:219], off
	v_lshl_add_u64 v[218:219], s[52:53], 0, v[162:163]
	s_mov_b32 m0, s57
	s_nop 0
	global_load_lds_dwordx4 v[218:219], off
	s_waitcnt vmcnt(8)
	s_waitcnt lgkmcnt(0)
	s_barrier
	s_waitcnt lgkmcnt(0)
	v_mfma_f32_16x16x32_bf16 v[140:143], v[48:51], v[180:183], v[140:143]
	v_mfma_f32_16x16x32_bf16 v[136:139], v[64:67], v[180:183], v[136:139]
	v_mfma_f32_16x16x32_bf16 v[124:127], v[48:51], v[188:191], v[124:127]
	v_mfma_f32_16x16x32_bf16 v[120:123], v[64:67], v[188:191], v[120:123]
	v_mfma_f32_16x16x32_bf16 v[108:111], v[48:51], v[196:199], v[108:111]
	v_mfma_f32_16x16x32_bf16 v[104:107], v[64:67], v[196:199], v[104:107]
	v_mfma_f32_16x16x32_bf16 v[92:95], v[48:51], v[204:207], v[92:95]
	v_mfma_f32_16x16x32_bf16 v[88:91], v[64:67], v[204:207], v[88:91]
	v_mfma_f32_16x16x32_bf16 v[140:143], v[52:55], v[184:187], v[140:143]
	v_mfma_f32_16x16x32_bf16 v[136:139], v[68:71], v[184:187], v[136:139]
	v_mfma_f32_16x16x32_bf16 v[124:127], v[52:55], v[192:195], v[124:127]
	v_mfma_f32_16x16x32_bf16 v[120:123], v[68:71], v[192:195], v[120:123]
	v_mfma_f32_16x16x32_bf16 v[108:111], v[52:55], v[200:203], v[108:111]
	v_mfma_f32_16x16x32_bf16 v[104:107], v[68:71], v[200:203], v[104:107]
	v_mfma_f32_16x16x32_bf16 v[92:95], v[52:55], v[208:211], v[92:95]
	v_mfma_f32_16x16x32_bf16 v[88:91], v[68:71], v[208:211], v[88:91]
	v_mfma_f32_16x16x32_bf16 v[132:135], v[146:149], v[180:183], v[132:135]
	v_mfma_f32_16x16x32_bf16 v[128:131], v[154:157], v[180:183], v[128:131]
	v_mfma_f32_16x16x32_bf16 v[116:119], v[146:149], v[188:191], v[116:119]
	v_mfma_f32_16x16x32_bf16 v[112:115], v[154:157], v[188:191], v[112:115]
	v_mfma_f32_16x16x32_bf16 v[100:103], v[146:149], v[196:199], v[100:103]
	v_mfma_f32_16x16x32_bf16 v[96:99], v[154:157], v[196:199], v[96:99]
	v_mfma_f32_16x16x32_bf16 v[84:87], v[146:149], v[204:207], v[84:87]
	v_mfma_f32_16x16x32_bf16 v[80:83], v[154:157], v[204:207], v[80:83]
	v_mfma_f32_16x16x32_bf16 v[132:135], v[150:153], v[184:187], v[132:135]
	v_mfma_f32_16x16x32_bf16 v[128:131], v[170:173], v[184:187], v[128:131]
	v_mfma_f32_16x16x32_bf16 v[116:119], v[150:153], v[192:195], v[116:119]
	v_mfma_f32_16x16x32_bf16 v[112:115], v[170:173], v[192:195], v[112:115]
	v_mfma_f32_16x16x32_bf16 v[100:103], v[150:153], v[200:203], v[100:103]
	v_mfma_f32_16x16x32_bf16 v[96:99], v[170:173], v[200:203], v[96:99]
	v_mfma_f32_16x16x32_bf16 v[84:87], v[150:153], v[208:211], v[84:87]
	v_mfma_f32_16x16x32_bf16 v[80:83], v[170:173], v[208:211], v[80:83]
	s_barrier
	s_add_i32 s52, s70, s27
	v_lshl_add_u64 v[174:175], v[174:175], 0, s[20:21]
	s_mov_b32 m0, s52
	ds_read_b128 v[180:183], v178 offset:49152
	ds_read_b128 v[184:187], v178 offset:50176
	ds_read_b128 v[188:191], v178 offset:51200
	ds_read_b128 v[192:195], v178 offset:52224
	ds_read_b128 v[196:199], v178 offset:53248
	ds_read_b128 v[200:203], v178 offset:54272
	ds_read_b128 v[204:207], v178 offset:55296
	ds_read_b128 v[208:211], v178 offset:56320
	global_load_lds_dwordx4 v[174:175], off
	s_add_i32 m0, s52, 0x2000
	s_add_u32 s50, s50, 0x40080
	v_lshl_add_u64 v[174:175], v[212:213], 0, s[20:21]
	s_addc_u32 s51, s51, 0
	s_add_i32 s52, s71, s27
	global_load_lds_dwordx4 v[174:175], off
	v_lshl_add_u64 v[174:175], s[50:51], 0, v[144:145]
	s_mov_b32 m0, s52
	s_nop 0
	global_load_lds_dwordx4 v[174:175], off
	v_lshl_add_u64 v[174:175], s[50:51], 0, v[164:165]
	s_add_i32 m0, s52, 0x2000
	s_nop 0
	global_load_lds_dwordx4 v[174:175], off
	v_lshl_add_u64 v[174:175], v[214:215], 0, s[20:21]
	s_mov_b32 m0, s60
	s_nop 0
	global_load_lds_dwordx4 v[174:175], off
	v_lshl_add_u64 v[174:175], v[216:217], 0, s[20:21]
	s_mov_b32 m0, s61
	s_nop 0
	global_load_lds_dwordx4 v[174:175], off
	s_waitcnt vmcnt(8)
	s_waitcnt lgkmcnt(0)
	s_barrier
	s_waitcnt lgkmcnt(0)
	v_mfma_f32_16x16x32_bf16 v[76:79], v[48:51], v[180:183], v[76:79]
	v_mfma_f32_16x16x32_bf16 v[72:75], v[64:67], v[180:183], v[72:75]
	v_mfma_f32_16x16x32_bf16 v[60:63], v[48:51], v[188:191], v[60:63]
	v_mfma_f32_16x16x32_bf16 v[56:59], v[64:67], v[188:191], v[56:59]
	v_mfma_f32_16x16x32_bf16 v[28:31], v[48:51], v[196:199], v[28:31]
	v_mfma_f32_16x16x32_bf16 v[24:27], v[64:67], v[196:199], v[24:27]
	v_mfma_f32_16x16x32_bf16 v[12:15], v[48:51], v[204:207], v[12:15]
	v_mfma_f32_16x16x32_bf16 v[8:11], v[64:67], v[204:207], v[8:11]
	v_mfma_f32_16x16x32_bf16 v[76:79], v[52:55], v[184:187], v[76:79]
	v_mfma_f32_16x16x32_bf16 v[72:75], v[68:71], v[184:187], v[72:75]
	v_mfma_f32_16x16x32_bf16 v[60:63], v[52:55], v[192:195], v[60:63]
	v_mfma_f32_16x16x32_bf16 v[56:59], v[68:71], v[192:195], v[56:59]
	v_mfma_f32_16x16x32_bf16 v[28:31], v[52:55], v[200:203], v[28:31]
	v_mfma_f32_16x16x32_bf16 v[24:27], v[68:71], v[200:203], v[24:27]
	v_mfma_f32_16x16x32_bf16 v[12:15], v[52:55], v[208:211], v[12:15]
	v_mfma_f32_16x16x32_bf16 v[8:11], v[68:71], v[208:211], v[8:11]
	v_mfma_f32_16x16x32_bf16 v[32:35], v[146:149], v[180:183], v[32:35]
	v_mfma_f32_16x16x32_bf16 v[68:71], v[150:153], v[184:187], v[32:35]
	v_mfma_f32_16x16x32_bf16 v[32:35], v[154:157], v[180:183], v[36:39]
	v_mfma_f32_16x16x32_bf16 v[64:67], v[170:173], v[184:187], v[32:35]
	v_mfma_f32_16x16x32_bf16 v[32:35], v[146:149], v[188:191], v[40:43]
	v_mfma_f32_16x16x32_bf16 v[52:55], v[150:153], v[192:195], v[32:35]
	v_mfma_f32_16x16x32_bf16 v[32:35], v[154:157], v[188:191], v[44:47]
	v_mfma_f32_16x16x32_bf16 v[20:23], v[146:149], v[196:199], v[20:23]
	v_mfma_f32_16x16x32_bf16 v[16:19], v[154:157], v[196:199], v[16:19]
	v_mfma_f32_16x16x32_bf16 v[4:7], v[146:149], v[204:207], v[4:7]
	v_mfma_f32_16x16x32_bf16 v[0:3], v[154:157], v[204:207], v[0:3]
	v_mfma_f32_16x16x32_bf16 v[48:51], v[170:173], v[192:195], v[32:35]
	v_mfma_f32_16x16x32_bf16 v[20:23], v[150:153], v[200:203], v[20:23]
	v_mfma_f32_16x16x32_bf16 v[16:19], v[170:173], v[200:203], v[16:19]
	v_mfma_f32_16x16x32_bf16 v[4:7], v[150:153], v[208:211], v[4:7]
	v_mfma_f32_16x16x32_bf16 v[0:3], v[170:173], v[208:211], v[0:3]
	s_barrier
	s_add_i32 s69, s69, 2
	s_add_u32 s40, s40, 0x100
	s_addc_u32 s41, s41, 0
	s_add_u32 s45, s45, 0x100
	s_addc_u32 s68, s68, 0
	s_cmp_gt_u32 s69, 13
	s_cbranch_scc0 .LBB0_625
	s_and_b64 vcc, exec, s[24:25]
	s_cbranch_vccz .LBB0_628
	s_barrier

.LBB0_737:
	s_ashr_i32 s25, s24, 31
	s_lshl_b64 s[42:43], s[24:25], 17
	s_add_u32 s42, s15, s42
	s_addc_u32 s43, s26, s43
	s_and_b64 s[44:45], s[36:37], exec
	s_cselect_b32 s53, s43, s47
	s_cselect_b32 s52, s42, s46
	s_ashr_i32 s39, s38, 31
	s_lshl_b64 s[44:45], s[38:39], 17
	s_add_u32 s44, s27, s44
	s_addc_u32 s45, s30, s45
	s_and_b64 s[48:49], s[36:37], exec
	s_cselect_b32 s49, s45, s51
	s_cselect_b32 s48, s44, s50
	s_add_i32 s25, 0, 0x10000
	s_add_i32 s39, 0, 0x14000
	v_add_u32_e32 v154, s25, v136
	v_add_u32_e32 v155, s39, v136
	ds_read_b128 v[0:3], v154
	ds_read_b128 v[4:7], v154 offset:1024
	ds_read_b128 v[8:11], v154 offset:2048
	ds_read_b128 v[12:15], v154 offset:3072
	ds_read_b128 v[16:19], v155
	ds_read_b128 v[20:23], v155 offset:1024
	ds_read_b128 v[24:27], v155 offset:2048
	ds_read_b128 v[28:31], v155 offset:3072
	s_add_u32 s64, s46, 0x10080
	s_addc_u32 s65, s47, 0
	s_add_i32 s69, s41, 0xc000
	v_lshl_add_u64 v[64:65], s[64:65], 0, v[132:133]
	s_mov_b32 m0, s69
	s_add_i32 s5, s41, 0xe000
	ds_read_b128 v[32:35], v137
	ds_read_b128 v[36:39], v137 offset:1024
	ds_read_b128 v[40:43], v137 offset:2048
	ds_read_b128 v[44:47], v137 offset:3072
	ds_read_b128 v[48:51], v137 offset:4096
	ds_read_b128 v[52:55], v137 offset:5120
	ds_read_b128 v[56:59], v137 offset:6144
	ds_read_b128 v[60:63], v137 offset:7168
	global_load_lds_dwordx4 v[64:65], off
	v_lshl_add_u64 v[64:65], s[64:65], 0, v[130:131]
	s_mov_b32 m0, s5
	s_nop 0
	global_load_lds_dwordx4 v[64:65], off
	s_waitcnt vmcnt(8)
	s_waitcnt lgkmcnt(0)
	s_barrier
	s_waitcnt lgkmcnt(0)
	v_mfma_f32_16x16x32_bf16 v[64:67], v[0:3], v[32:35], 0
	v_mfma_f32_16x16x32_bf16 v[68:71], v[8:11], v[32:35], 0
	v_mfma_f32_16x16x32_bf16 v[72:75], v[0:3], v[40:43], 0
	v_mfma_f32_16x16x32_bf16 v[76:79], v[8:11], v[40:43], 0
	v_mfma_f32_16x16x32_bf16 v[80:83], v[0:3], v[48:51], 0
	v_mfma_f32_16x16x32_bf16 v[84:87], v[8:11], v[48:51], 0
	v_mfma_f32_16x16x32_bf16 v[88:91], v[0:3], v[56:59], 0
	v_mfma_f32_16x16x32_bf16 v[92:95], v[8:11], v[56:59], 0
	v_mfma_f32_16x16x32_bf16 v[64:67], v[4:7], v[36:39], v[64:67]
	v_mfma_f32_16x16x32_bf16 v[68:71], v[12:15], v[36:39], v[68:71]
	v_mfma_f32_16x16x32_bf16 v[72:75], v[4:7], v[44:47], v[72:75]
	v_mfma_f32_16x16x32_bf16 v[76:79], v[12:15], v[44:47], v[76:79]
	v_mfma_f32_16x16x32_bf16 v[80:83], v[4:7], v[52:55], v[80:83]
	v_mfma_f32_16x16x32_bf16 v[84:87], v[12:15], v[52:55], v[84:87]
	v_mfma_f32_16x16x32_bf16 v[88:91], v[4:7], v[60:63], v[88:91]
	v_mfma_f32_16x16x32_bf16 v[92:95], v[12:15], v[60:63], v[92:95]
	v_mfma_f32_16x16x32_bf16 v[96:99], v[16:19], v[32:35], 0
	v_mfma_f32_16x16x32_bf16 v[32:35], v[24:27], v[32:35], 0
	v_mfma_f32_16x16x32_bf16 v[96:99], v[20:23], v[36:39], v[96:99]
	v_mfma_f32_16x16x32_bf16 v[32:35], v[28:31], v[36:39], v[32:35]
	v_mfma_f32_16x16x32_bf16 v[36:39], v[16:19], v[40:43], 0
	v_mfma_f32_16x16x32_bf16 v[40:43], v[24:27], v[40:43], 0
	v_mfma_f32_16x16x32_bf16 v[36:39], v[20:23], v[44:47], v[36:39]
	v_mfma_f32_16x16x32_bf16 v[40:43], v[28:31], v[44:47], v[40:43]
	v_mfma_f32_16x16x32_bf16 v[44:47], v[16:19], v[48:51], 0
	v_mfma_f32_16x16x32_bf16 v[48:51], v[24:27], v[48:51], 0
	v_mfma_f32_16x16x32_bf16 v[44:47], v[20:23], v[52:55], v[44:47]
	v_mfma_f32_16x16x32_bf16 v[48:51], v[28:31], v[52:55], v[48:51]
	v_mfma_f32_16x16x32_bf16 v[52:55], v[16:19], v[56:59], 0
	v_mfma_f32_16x16x32_bf16 v[56:59], v[24:27], v[56:59], 0
	v_mfma_f32_16x16x32_bf16 v[52:55], v[20:23], v[60:63], v[52:55]
	v_mfma_f32_16x16x32_bf16 v[56:59], v[28:31], v[60:63], v[56:59]
	s_barrier
	s_add_i32 s65, s25, s54
	v_lshl_add_u64 v[142:143], s[50:51], 0, v[144:145]
	s_mov_b64 s[72:73], 0x100
	s_add_i32 s25, s65, 0x2000
	v_lshl_add_u64 v[138:139], v[142:143], 0, s[72:73]
	s_mov_b32 m0, s65
	v_lshl_add_u64 v[146:147], s[50:51], 0, v[128:129]
	s_add_u32 s70, s50, 0x10100
	ds_read_b128 v[60:63], v137 offset:16384
	ds_read_b128 v[100:103], v137 offset:17408
	ds_read_b128 v[104:107], v137 offset:18432
	ds_read_b128 v[108:111], v137 offset:19456
	ds_read_b128 v[112:115], v137 offset:20480
	ds_read_b128 v[116:119], v137 offset:21504
	ds_read_b128 v[120:123], v137 offset:22528
	ds_read_b128 v[124:127], v137 offset:23552
	global_load_lds_dwordx4 v[138:139], off
	v_lshl_add_u64 v[138:139], v[146:147], 0, s[72:73]
	s_mov_b32 m0, s25
	s_addc_u32 s71, s51, 0
	s_add_i32 s39, s39, s54
	global_load_lds_dwordx4 v[138:139], off
	v_lshl_add_u64 v[138:139], s[70:71], 0, v[144:145]
	s_mov_b32 m0, s39
	s_add_i32 s64, s39, 0x2000
	global_load_lds_dwordx4 v[138:139], off
	v_lshl_add_u64 v[138:139], s[70:71], 0, v[128:129]
	s_mov_b32 m0, s64
	v_lshl_add_u64 v[148:149], s[46:47], 0, v[132:133]
	global_load_lds_dwordx4 v[138:139], off
	v_lshl_add_u64 v[138:139], v[148:149], 0, s[72:73]
	s_mov_b32 m0, s41
	v_lshl_add_u64 v[150:151], s[46:47], 0, v[130:131]
	global_load_lds_dwordx4 v[138:139], off
	v_lshl_add_u64 v[138:139], v[150:151], 0, s[72:73]
	s_mov_b32 m0, s55
	s_nop 0
	global_load_lds_dwordx4 v[138:139], off
	s_waitcnt vmcnt(8)
	s_waitcnt lgkmcnt(0)
	s_barrier
	s_waitcnt lgkmcnt(0)
	v_mfma_f32_16x16x32_bf16 v[138:141], v[0:3], v[60:63], 0
	v_mfma_f32_16x16x32_bf16 v[164:167], v[0:3], v[104:107], 0
	v_mfma_f32_16x16x32_bf16 v[172:175], v[0:3], v[112:115], 0
	v_mfma_f32_16x16x32_bf16 v[0:3], v[0:3], v[120:123], 0
	v_mfma_f32_16x16x32_bf16 v[138:141], v[4:7], v[100:103], v[138:141]
	v_mfma_f32_16x16x32_bf16 v[164:167], v[4:7], v[108:111], v[164:167]
	v_mfma_f32_16x16x32_bf16 v[172:175], v[4:7], v[116:119], v[172:175]
	v_mfma_f32_16x16x32_bf16 v[0:3], v[4:7], v[124:127], v[0:3]
	v_mfma_f32_16x16x32_bf16 v[4:7], v[8:11], v[120:123], 0
	v_mfma_f32_16x16x32_bf16 v[160:163], v[8:11], v[60:63], 0
	v_mfma_f32_16x16x32_bf16 v[168:171], v[8:11], v[104:107], 0
	v_mfma_f32_16x16x32_bf16 v[176:179], v[8:11], v[112:115], 0
	v_mfma_f32_16x16x32_bf16 v[4:7], v[12:15], v[124:127], v[4:7]
	v_mfma_f32_16x16x32_bf16 v[160:163], v[12:15], v[100:103], v[160:163]
	v_mfma_f32_16x16x32_bf16 v[168:171], v[12:15], v[108:111], v[168:171]
	v_mfma_f32_16x16x32_bf16 v[176:179], v[12:15], v[116:119], v[176:179]
	v_mfma_f32_16x16x32_bf16 v[8:11], v[16:19], v[60:63], 0
	v_mfma_f32_16x16x32_bf16 v[12:15], v[24:27], v[60:63], 0
	v_mfma_f32_16x16x32_bf16 v[8:11], v[20:23], v[100:103], v[8:11]
	v_mfma_f32_16x16x32_bf16 v[12:15], v[28:31], v[100:103], v[12:15]
	v_mfma_f32_16x16x32_bf16 v[60:63], v[16:19], v[104:107], 0
	v_mfma_f32_16x16x32_bf16 v[100:103], v[24:27], v[104:107], 0
	v_mfma_f32_16x16x32_bf16 v[104:107], v[16:19], v[112:115], 0
	v_mfma_f32_16x16x32_bf16 v[16:19], v[16:19], v[120:123], 0
	v_mfma_f32_16x16x32_bf16 v[60:63], v[20:23], v[108:111], v[60:63]
	v_mfma_f32_16x16x32_bf16 v[100:103], v[28:31], v[108:111], v[100:103]
	v_mfma_f32_16x16x32_bf16 v[104:107], v[20:23], v[116:119], v[104:107]
	v_mfma_f32_16x16x32_bf16 v[108:111], v[24:27], v[112:115], 0
	v_mfma_f32_16x16x32_bf16 v[16:19], v[20:23], v[124:127], v[16:19]
	v_mfma_f32_16x16x32_bf16 v[20:23], v[24:27], v[120:123], 0
	v_mfma_f32_16x16x32_bf16 v[108:111], v[28:31], v[116:119], v[108:111]
	v_mfma_f32_16x16x32_bf16 v[20:23], v[28:31], v[124:127], v[20:23]
	s_barrier
	s_add_i32 s68, 0, 0x18000
	s_add_i32 s74, 0, 0x1c000
	v_add_u32_e32 v156, s68, v136
	v_add_u32_e32 v157, s74, v136
	ds_read_b128 v[24:27], v156
	ds_read_b128 v[28:31], v156 offset:1024
	ds_read_b128 v[112:115], v156 offset:2048
	ds_read_b128 v[116:119], v156 offset:3072
	ds_read_b128 v[120:123], v157
	ds_read_b128 v[124:127], v157 offset:1024
	ds_read_b128 v[180:183], v157 offset:2048
	ds_read_b128 v[184:187], v157 offset:3072
	s_add_u32 s70, s46, 0x10100
	s_addc_u32 s71, s47, 0
	s_mov_b32 m0, s56
	v_lshl_add_u64 v[152:153], s[70:71], 0, v[132:133]
	ds_read_b128 v[188:191], v137 offset:32768
	ds_read_b128 v[192:195], v137 offset:33792
	ds_read_b128 v[196:199], v137 offset:34816
	ds_read_b128 v[200:203], v137 offset:35840
	ds_read_b128 v[204:207], v137 offset:36864
	ds_read_b128 v[208:211], v137 offset:37888
	ds_read_b128 v[212:215], v137 offset:38912
	ds_read_b128 v[216:219], v137 offset:39936
	global_load_lds_dwordx4 v[152:153], off
	v_lshl_add_u64 v[152:153], s[70:71], 0, v[130:131]
	s_mov_b32 m0, s57
	s_nop 0
	global_load_lds_dwordx4 v[152:153], off
	s_waitcnt vmcnt(8)
	s_waitcnt lgkmcnt(0)
	s_barrier
	s_waitcnt lgkmcnt(0)
	v_mfma_f32_16x16x32_bf16 v[64:67], v[24:27], v[188:191], v[64:67]
	v_mfma_f32_16x16x32_bf16 v[68:71], v[112:115], v[188:191], v[68:71]
	v_mfma_f32_16x16x32_bf16 v[72:75], v[24:27], v[196:199], v[72:75]
	v_mfma_f32_16x16x32_bf16 v[76:79], v[112:115], v[196:199], v[76:79]
	v_mfma_f32_16x16x32_bf16 v[80:83], v[24:27], v[204:207], v[80:83]
	v_mfma_f32_16x16x32_bf16 v[84:87], v[112:115], v[204:207], v[84:87]
	v_mfma_f32_16x16x32_bf16 v[88:91], v[24:27], v[212:215], v[88:91]
	v_mfma_f32_16x16x32_bf16 v[92:95], v[112:115], v[212:215], v[92:95]
	v_mfma_f32_16x16x32_bf16 v[64:67], v[28:31], v[192:195], v[64:67]
	v_mfma_f32_16x16x32_bf16 v[68:71], v[116:119], v[192:195], v[68:71]
	v_mfma_f32_16x16x32_bf16 v[72:75], v[28:31], v[200:203], v[72:75]
	v_mfma_f32_16x16x32_bf16 v[76:79], v[116:119], v[200:203], v[76:79]
	v_mfma_f32_16x16x32_bf16 v[80:83], v[28:31], v[208:211], v[80:83]
	v_mfma_f32_16x16x32_bf16 v[84:87], v[116:119], v[208:211], v[84:87]
	v_mfma_f32_16x16x32_bf16 v[88:91], v[28:31], v[216:219], v[88:91]
	v_mfma_f32_16x16x32_bf16 v[92:95], v[116:119], v[216:219], v[92:95]
	v_mfma_f32_16x16x32_bf16 v[96:99], v[120:123], v[188:191], v[96:99]
	v_mfma_f32_16x16x32_bf16 v[32:35], v[180:183], v[188:191], v[32:35]
	v_mfma_f32_16x16x32_bf16 v[36:39], v[120:123], v[196:199], v[36:39]
	v_mfma_f32_16x16x32_bf16 v[40:43], v[180:183], v[196:199], v[40:43]
	v_mfma_f32_16x16x32_bf16 v[44:47], v[120:123], v[204:207], v[44:47]
	v_mfma_f32_16x16x32_bf16 v[48:51], v[180:183], v[204:207], v[48:51]
	v_mfma_f32_16x16x32_bf16 v[52:55], v[120:123], v[212:215], v[52:55]
	v_mfma_f32_16x16x32_bf16 v[56:59], v[180:183], v[212:215], v[56:59]
	v_mfma_f32_16x16x32_bf16 v[96:99], v[124:127], v[192:195], v[96:99]
	v_mfma_f32_16x16x32_bf16 v[32:35], v[184:187], v[192:195], v[32:35]
	v_mfma_f32_16x16x32_bf16 v[36:39], v[124:127], v[200:203], v[36:39]
	v_mfma_f32_16x16x32_bf16 v[40:43], v[184:187], v[200:203], v[40:43]
	v_mfma_f32_16x16x32_bf16 v[44:47], v[124:127], v[208:211], v[44:47]
	v_mfma_f32_16x16x32_bf16 v[48:51], v[184:187], v[208:211], v[48:51]
	v_mfma_f32_16x16x32_bf16 v[52:55], v[124:127], v[216:219], v[52:55]
	v_mfma_f32_16x16x32_bf16 v[56:59], v[184:187], v[216:219], v[56:59]
	s_barrier
	s_add_i32 s70, s68, s54
	s_mov_b64 vcc, 0x180
	s_add_i32 s68, s70, 0x2000
	v_lshl_add_u64 v[142:143], v[142:143], 0, vcc
	s_mov_b32 m0, s70
	s_add_u32 s72, s50, 0x10180
	ds_read_b128 v[188:191], v137 offset:49152
	ds_read_b128 v[192:195], v137 offset:50176
	ds_read_b128 v[196:199], v137 offset:51200
	ds_read_b128 v[200:203], v137 offset:52224
	ds_read_b128 v[204:207], v137 offset:53248
	ds_read_b128 v[208:211], v137 offset:54272
	ds_read_b128 v[212:215], v137 offset:55296
	ds_read_b128 v[216:219], v137 offset:56320
	global_load_lds_dwordx4 v[142:143], off
	v_lshl_add_u64 v[142:143], v[146:147], 0, vcc
	s_mov_b32 m0, s68
	s_addc_u32 s73, s51, 0
	s_add_i32 s50, s74, s54
	global_load_lds_dwordx4 v[142:143], off
	v_lshl_add_u64 v[142:143], s[72:73], 0, v[144:145]
	s_mov_b32 m0, s50
	s_add_i32 s51, s50, 0x2000
	global_load_lds_dwordx4 v[142:143], off
	v_lshl_add_u64 v[142:143], s[72:73], 0, v[128:129]
	s_mov_b32 m0, s51
	s_nop 0
	global_load_lds_dwordx4 v[142:143], off
	v_lshl_add_u64 v[142:143], v[148:149], 0, vcc
	s_mov_b32 m0, s60
	s_nop 0
	global_load_lds_dwordx4 v[142:143], off
	v_lshl_add_u64 v[142:143], v[150:151], 0, vcc
	s_mov_b32 m0, s61
	s_nop 0
	global_load_lds_dwordx4 v[142:143], off
	s_waitcnt vmcnt(8)
	s_waitcnt lgkmcnt(0)
	s_barrier
	s_waitcnt lgkmcnt(0)
	v_mfma_f32_16x16x32_bf16 v[0:3], v[24:27], v[212:215], v[0:3]
	v_mfma_f32_16x16x32_bf16 v[4:7], v[112:115], v[212:215], v[4:7]
	v_mfma_f32_16x16x32_bf16 v[138:141], v[24:27], v[188:191], v[138:141]
	v_mfma_f32_16x16x32_bf16 v[160:163], v[112:115], v[188:191], v[160:163]
	v_mfma_f32_16x16x32_bf16 v[164:167], v[24:27], v[196:199], v[164:167]
	v_mfma_f32_16x16x32_bf16 v[168:171], v[112:115], v[196:199], v[168:171]
	v_mfma_f32_16x16x32_bf16 v[172:175], v[24:27], v[204:207], v[172:175]
	v_mfma_f32_16x16x32_bf16 v[176:179], v[112:115], v[204:207], v[176:179]
	v_mfma_f32_16x16x32_bf16 v[0:3], v[28:31], v[216:219], v[0:3]
	v_mfma_f32_16x16x32_bf16 v[4:7], v[116:119], v[216:219], v[4:7]
	v_mfma_f32_16x16x32_bf16 v[138:141], v[28:31], v[192:195], v[138:141]
	v_mfma_f32_16x16x32_bf16 v[160:163], v[116:119], v[192:195], v[160:163]
	v_mfma_f32_16x16x32_bf16 v[164:167], v[28:31], v[200:203], v[164:167]
	v_mfma_f32_16x16x32_bf16 v[168:171], v[116:119], v[200:203], v[168:171]
	v_mfma_f32_16x16x32_bf16 v[172:175], v[28:31], v[208:211], v[172:175]
	v_mfma_f32_16x16x32_bf16 v[176:179], v[116:119], v[208:211], v[176:179]
	v_mfma_f32_16x16x32_bf16 v[8:11], v[120:123], v[188:191], v[8:11]
	v_mfma_f32_16x16x32_bf16 v[12:15], v[180:183], v[188:191], v[12:15]
	v_mfma_f32_16x16x32_bf16 v[24:27], v[120:123], v[196:199], v[60:63]
	v_mfma_f32_16x16x32_bf16 v[28:31], v[180:183], v[196:199], v[100:103]
	v_mfma_f32_16x16x32_bf16 v[60:63], v[120:123], v[204:207], v[104:107]
	v_mfma_f32_16x16x32_bf16 v[100:103], v[180:183], v[204:207], v[108:111]
	v_mfma_f32_16x16x32_bf16 v[16:19], v[120:123], v[212:215], v[16:19]
	v_mfma_f32_16x16x32_bf16 v[20:23], v[180:183], v[212:215], v[20:23]
	v_mfma_f32_16x16x32_bf16 v[8:11], v[124:127], v[192:195], v[8:11]
	v_mfma_f32_16x16x32_bf16 v[12:15], v[184:187], v[192:195], v[12:15]
	v_mfma_f32_16x16x32_bf16 v[24:27], v[124:127], v[200:203], v[24:27]
	v_mfma_f32_16x16x32_bf16 v[28:31], v[184:187], v[200:203], v[28:31]
	v_mfma_f32_16x16x32_bf16 v[60:63], v[124:127], v[208:211], v[60:63]
	v_mfma_f32_16x16x32_bf16 v[100:103], v[184:187], v[208:211], v[100:103]
	v_mfma_f32_16x16x32_bf16 v[16:19], v[124:127], v[216:219], v[16:19]
	v_mfma_f32_16x16x32_bf16 v[20:23], v[184:187], v[216:219], v[20:23]
	s_barrier
	ds_read_b128 v[104:107], v154
	ds_read_b128 v[108:111], v154 offset:1024
	ds_read_b128 v[112:115], v154 offset:2048
	ds_read_b128 v[116:119], v154 offset:3072
	ds_read_b128 v[120:123], v155
	ds_read_b128 v[124:127], v155 offset:1024
	ds_read_b128 v[180:183], v155 offset:2048
	ds_read_b128 v[184:187], v155 offset:3072
	s_add_u32 s46, s46, 0x10180
	s_addc_u32 s47, s47, 0
	s_mov_b32 m0, s69
	v_lshl_add_u64 v[142:143], s[46:47], 0, v[132:133]
	ds_read_b128 v[188:191], v137
	ds_read_b128 v[192:195], v137 offset:1024
	ds_read_b128 v[196:199], v137 offset:2048
	ds_read_b128 v[200:203], v137 offset:3072
	ds_read_b128 v[204:207], v137 offset:4096
	ds_read_b128 v[208:211], v137 offset:5120
	ds_read_b128 v[212:215], v137 offset:6144
	ds_read_b128 v[216:219], v137 offset:7168
	global_load_lds_dwordx4 v[142:143], off
	v_lshl_add_u64 v[142:143], s[46:47], 0, v[130:131]
	s_mov_b32 m0, s5
	s_nop 0
	global_load_lds_dwordx4 v[142:143], off
	s_waitcnt vmcnt(8)
	s_waitcnt lgkmcnt(0)
	s_barrier
	s_waitcnt lgkmcnt(0)
	v_mfma_f32_16x16x32_bf16 v[64:67], v[104:107], v[188:191], v[64:67]
	v_mfma_f32_16x16x32_bf16 v[68:71], v[112:115], v[188:191], v[68:71]
	v_mfma_f32_16x16x32_bf16 v[72:75], v[104:107], v[196:199], v[72:75]
	v_mfma_f32_16x16x32_bf16 v[76:79], v[112:115], v[196:199], v[76:79]
	v_mfma_f32_16x16x32_bf16 v[80:83], v[104:107], v[204:207], v[80:83]
	v_mfma_f32_16x16x32_bf16 v[84:87], v[112:115], v[204:207], v[84:87]
	v_mfma_f32_16x16x32_bf16 v[88:91], v[104:107], v[212:215], v[88:91]
	v_mfma_f32_16x16x32_bf16 v[92:95], v[112:115], v[212:215], v[92:95]
	v_mfma_f32_16x16x32_bf16 v[64:67], v[108:111], v[192:195], v[64:67]
	v_mfma_f32_16x16x32_bf16 v[68:71], v[116:119], v[192:195], v[68:71]
	v_mfma_f32_16x16x32_bf16 v[72:75], v[108:111], v[200:203], v[72:75]
	v_mfma_f32_16x16x32_bf16 v[76:79], v[116:119], v[200:203], v[76:79]
	v_mfma_f32_16x16x32_bf16 v[80:83], v[108:111], v[208:211], v[80:83]
	v_mfma_f32_16x16x32_bf16 v[84:87], v[116:119], v[208:211], v[84:87]
	v_mfma_f32_16x16x32_bf16 v[88:91], v[108:111], v[216:219], v[88:91]
	v_mfma_f32_16x16x32_bf16 v[92:95], v[116:119], v[216:219], v[92:95]
	v_mfma_f32_16x16x32_bf16 v[32:35], v[180:183], v[188:191], v[32:35]
	v_mfma_f32_16x16x32_bf16 v[96:99], v[120:123], v[188:191], v[96:99]
	v_mfma_f32_16x16x32_bf16 v[188:191], v[184:187], v[192:195], v[32:35]
	v_mfma_f32_16x16x32_bf16 v[32:35], v[120:123], v[196:199], v[36:39]
	v_mfma_f32_16x16x32_bf16 v[220:223], v[124:127], v[192:195], v[96:99]
	v_mfma_f32_16x16x32_bf16 v[192:195], v[124:127], v[200:203], v[32:35]
	v_mfma_f32_16x16x32_bf16 v[32:35], v[180:183], v[196:199], v[40:43]
	v_mfma_f32_16x16x32_bf16 v[40:43], v[184:187], v[200:203], v[32:35]
	v_mfma_f32_16x16x32_bf16 v[32:35], v[120:123], v[204:207], v[44:47]
	v_mfma_f32_16x16x32_bf16 v[44:47], v[124:127], v[208:211], v[32:35]
	v_mfma_f32_16x16x32_bf16 v[32:35], v[180:183], v[204:207], v[48:51]
	v_mfma_f32_16x16x32_bf16 v[48:51], v[184:187], v[208:211], v[32:35]
	v_mfma_f32_16x16x32_bf16 v[32:35], v[120:123], v[212:215], v[52:55]
	v_mfma_f32_16x16x32_bf16 v[52:55], v[124:127], v[216:219], v[32:35]
	v_mfma_f32_16x16x32_bf16 v[32:35], v[180:183], v[212:215], v[56:59]
	v_mfma_f32_16x16x32_bf16 v[56:59], v[184:187], v[216:219], v[32:35]
	s_barrier
	s_mov_b32 m0, s65
	v_lshl_add_u64 v[142:143], s[48:49], 0, v[144:145]
	s_add_u32 s46, s48, 0x10000
	s_nop 1
	ds_read_b128 v[32:35], v137 offset:16384
	ds_read_b128 v[36:39], v137 offset:17408
	ds_read_b128 v[96:99], v137 offset:18432
	ds_read_b128 v[196:199], v137 offset:19456
	ds_read_b128 v[200:203], v137 offset:20480
	ds_read_b128 v[204:207], v137 offset:21504
	ds_read_b128 v[208:211], v137 offset:22528
	ds_read_b128 v[212:215], v137 offset:23552
	global_load_lds_dwordx4 v[142:143], off
	v_lshl_add_u64 v[250:251], s[48:49], 0, v[128:129]
	s_mov_b32 m0, s25
	s_addc_u32 s47, s49, 0
	global_load_lds_dwordx4 v[250:251], off
	v_lshl_add_u64 v[146:147], s[46:47], 0, v[144:145]
	s_mov_b32 m0, s39
	v_lshl_add_u64 v[244:245], s[52:53], 0, v[132:133]
	global_load_lds_dwordx4 v[146:147], off
	v_lshl_add_u64 v[146:147], s[46:47], 0, v[128:129]
	s_mov_b32 m0, s64
	v_lshl_add_u64 v[242:243], s[52:53], 0, v[130:131]
	global_load_lds_dwordx4 v[146:147], off
	s_mov_b32 m0, s41
	s_nop 0
	global_load_lds_dwordx4 v[244:245], off
	s_mov_b32 m0, s55
	s_nop 0
	global_load_lds_dwordx4 v[242:243], off
	s_waitcnt vmcnt(8)
	s_waitcnt lgkmcnt(0)
	s_barrier
	s_waitcnt lgkmcnt(0)
	v_mfma_f32_16x16x32_bf16 v[0:3], v[104:107], v[208:211], v[0:3]
	v_mfma_f32_16x16x32_bf16 v[4:7], v[112:115], v[208:211], v[4:7]
	v_mfma_f32_16x16x32_bf16 v[138:141], v[104:107], v[32:35], v[138:141]
	v_mfma_f32_16x16x32_bf16 v[160:163], v[112:115], v[32:35], v[160:163]
	v_mfma_f32_16x16x32_bf16 v[164:167], v[104:107], v[96:99], v[164:167]
	v_mfma_f32_16x16x32_bf16 v[168:171], v[112:115], v[96:99], v[168:171]
	v_mfma_f32_16x16x32_bf16 v[172:175], v[104:107], v[200:203], v[172:175]
	v_mfma_f32_16x16x32_bf16 v[176:179], v[112:115], v[200:203], v[176:179]
	v_mfma_f32_16x16x32_bf16 v[0:3], v[108:111], v[212:215], v[0:3]
	v_mfma_f32_16x16x32_bf16 v[4:7], v[116:119], v[212:215], v[4:7]
	v_mfma_f32_16x16x32_bf16 v[138:141], v[108:111], v[36:39], v[138:141]
	v_mfma_f32_16x16x32_bf16 v[160:163], v[116:119], v[36:39], v[160:163]
	v_mfma_f32_16x16x32_bf16 v[164:167], v[108:111], v[196:199], v[164:167]
	v_mfma_f32_16x16x32_bf16 v[168:171], v[116:119], v[196:199], v[168:171]
	v_mfma_f32_16x16x32_bf16 v[172:175], v[108:111], v[204:207], v[172:175]
	v_mfma_f32_16x16x32_bf16 v[176:179], v[116:119], v[204:207], v[176:179]
	v_mfma_f32_16x16x32_bf16 v[8:11], v[120:123], v[32:35], v[8:11]
	v_mfma_f32_16x16x32_bf16 v[12:15], v[180:183], v[32:35], v[12:15]
	v_mfma_f32_16x16x32_bf16 v[24:27], v[120:123], v[96:99], v[24:27]
	v_mfma_f32_16x16x32_bf16 v[28:31], v[180:183], v[96:99], v[28:31]
	v_mfma_f32_16x16x32_bf16 v[32:35], v[120:123], v[200:203], v[60:63]
	v_mfma_f32_16x16x32_bf16 v[24:27], v[124:127], v[196:199], v[24:27]
	v_mfma_f32_16x16x32_bf16 v[28:31], v[184:187], v[196:199], v[28:31]
	v_mfma_f32_16x16x32_bf16 v[196:199], v[124:127], v[204:207], v[32:35]
	v_mfma_f32_16x16x32_bf16 v[32:35], v[180:183], v[200:203], v[100:103]
	v_mfma_f32_16x16x32_bf16 v[16:19], v[120:123], v[208:211], v[16:19]
	v_mfma_f32_16x16x32_bf16 v[8:11], v[124:127], v[36:39], v[8:11]
	v_mfma_f32_16x16x32_bf16 v[12:15], v[184:187], v[36:39], v[12:15]
	v_mfma_f32_16x16x32_bf16 v[200:203], v[184:187], v[204:207], v[32:35]
	v_mfma_f32_16x16x32_bf16 v[204:207], v[124:127], v[212:215], v[16:19]
	v_mfma_f32_16x16x32_bf16 v[16:19], v[180:183], v[208:211], v[20:23]
	v_mfma_f32_16x16x32_bf16 v[180:183], v[184:187], v[212:215], v[16:19]
	s_barrier
	ds_read_b128 v[60:63], v156
	ds_read_b128 v[184:187], v156 offset:1024
	ds_read_b128 v[208:211], v156 offset:2048
	ds_read_b128 v[212:215], v156 offset:3072
	ds_read_b128 v[216:219], v157
	ds_read_b128 v[224:227], v157 offset:1024
	ds_read_b128 v[228:231], v157 offset:2048
	ds_read_b128 v[232:235], v157 offset:3072
	s_add_u32 s46, s52, 0x10000
	s_addc_u32 s47, s53, 0
	s_mov_b32 m0, s56
	v_lshl_add_u64 v[32:33], s[46:47], 0, v[132:133]
	ds_read_b128 v[16:19], v137 offset:32768
	ds_read_b128 v[20:23], v137 offset:33792
	ds_read_b128 v[108:111], v137 offset:34816
	ds_read_b128 v[236:239], v137 offset:35840
	ds_read_b128 v[246:249], v137 offset:36864
	ds_read_b128 v[146:149], v137 offset:37888
	ds_read_b128 v[150:153], v137 offset:38912
	ds_read_b128 v[154:157], v137 offset:39936
	global_load_lds_dwordx4 v[32:33], off
	v_lshl_add_u64 v[32:33], s[46:47], 0, v[130:131]
	s_mov_b32 m0, s57
	s_nop 0
	global_load_lds_dwordx4 v[32:33], off
	s_waitcnt vmcnt(8)
	s_waitcnt lgkmcnt(0)
	s_barrier
	s_waitcnt lgkmcnt(0)
	v_mfma_f32_16x16x32_bf16 v[32:35], v[60:63], v[16:19], v[64:67]
	v_mfma_f32_16x16x32_bf16 v[112:115], v[184:187], v[20:23], v[32:35]
	v_mfma_f32_16x16x32_bf16 v[32:35], v[208:211], v[16:19], v[68:71]
	v_mfma_f32_16x16x32_bf16 v[116:119], v[212:215], v[20:23], v[32:35]
	v_mfma_f32_16x16x32_bf16 v[32:35], v[60:63], v[108:111], v[72:75]
	v_mfma_f32_16x16x32_bf16 v[96:99], v[184:187], v[236:239], v[32:35]
	v_mfma_f32_16x16x32_bf16 v[32:35], v[208:211], v[108:111], v[76:79]
	v_mfma_f32_16x16x32_bf16 v[100:103], v[212:215], v[236:239], v[32:35]
	v_mfma_f32_16x16x32_bf16 v[32:35], v[60:63], v[246:249], v[80:83]
	v_mfma_f32_16x16x32_bf16 v[64:67], v[184:187], v[146:149], v[32:35]
	v_mfma_f32_16x16x32_bf16 v[32:35], v[208:211], v[246:249], v[84:87]
	v_mfma_f32_16x16x32_bf16 v[68:71], v[212:215], v[146:149], v[32:35]
	v_mfma_f32_16x16x32_bf16 v[32:35], v[60:63], v[150:153], v[88:91]
	v_mfma_f32_16x16x32_bf16 v[36:39], v[208:211], v[150:153], v[92:95]
	v_mfma_f32_16x16x32_bf16 v[32:35], v[184:187], v[154:157], v[32:35]
	v_mfma_f32_16x16x32_bf16 v[36:39], v[212:215], v[154:157], v[36:39]
	v_mfma_f32_16x16x32_bf16 v[72:75], v[216:219], v[16:19], v[220:223]
	v_mfma_f32_16x16x32_bf16 v[16:19], v[228:231], v[16:19], v[188:191]
	v_mfma_f32_16x16x32_bf16 v[124:127], v[232:235], v[20:23], v[16:19]
	v_mfma_f32_16x16x32_bf16 v[16:19], v[216:219], v[108:111], v[192:195]
	v_mfma_f32_16x16x32_bf16 v[104:107], v[224:227], v[236:239], v[16:19]
	v_mfma_f32_16x16x32_bf16 v[16:19], v[228:231], v[108:111], v[40:43]
	v_mfma_f32_16x16x32_bf16 v[108:111], v[232:235], v[236:239], v[16:19]
	v_mfma_f32_16x16x32_bf16 v[16:19], v[216:219], v[246:249], v[44:47]
	v_mfma_f32_16x16x32_bf16 v[120:123], v[224:227], v[20:23], v[72:75]
	v_mfma_f32_16x16x32_bf16 v[72:75], v[224:227], v[146:149], v[16:19]
	v_mfma_f32_16x16x32_bf16 v[16:19], v[228:231], v[246:249], v[48:51]
	v_mfma_f32_16x16x32_bf16 v[76:79], v[232:235], v[146:149], v[16:19]
	v_mfma_f32_16x16x32_bf16 v[16:19], v[216:219], v[150:153], v[52:55]
	v_mfma_f32_16x16x32_bf16 v[40:43], v[224:227], v[154:157], v[16:19]
	v_mfma_f32_16x16x32_bf16 v[16:19], v[228:231], v[150:153], v[56:59]
	v_mfma_f32_16x16x32_bf16 v[44:47], v[232:235], v[154:157], v[16:19]
	s_barrier
	s_mov_b32 m0, s70
	s_nop 3
	v_lshl_add_u64 v[16:17], v[142:143], 0, s[20:21]
	s_add_u32 s46, s48, 0x10080
	ds_read_b128 v[56:59], v137 offset:49152
	ds_read_b128 v[92:95], v137 offset:50176
	ds_read_b128 v[146:149], v137 offset:51200
	ds_read_b128 v[150:153], v137 offset:52224
	ds_read_b128 v[154:157], v137 offset:53248
	ds_read_b128 v[188:191], v137 offset:54272
	ds_read_b128 v[192:195], v137 offset:55296
	ds_read_b128 v[220:223], v137 offset:56320
	global_load_lds_dwordx4 v[16:17], off
	v_lshl_add_u64 v[16:17], v[250:251], 0, s[20:21]
	s_mov_b32 m0, s68
	s_addc_u32 s47, s49, 0
	global_load_lds_dwordx4 v[16:17], off
	v_lshl_add_u64 v[16:17], s[46:47], 0, v[144:145]
	s_mov_b32 m0, s50
	s_nop 0
	global_load_lds_dwordx4 v[16:17], off
	v_lshl_add_u64 v[16:17], s[46:47], 0, v[128:129]
	s_mov_b32 m0, s51
	s_nop 0
	global_load_lds_dwordx4 v[16:17], off
	v_lshl_add_u64 v[16:17], v[244:245], 0, s[20:21]
	s_mov_b32 m0, s60
	s_nop 0
	global_load_lds_dwordx4 v[16:17], off
	v_lshl_add_u64 v[16:17], v[242:243], 0, s[20:21]
	s_mov_b32 m0, s61
	s_nop 0
	global_load_lds_dwordx4 v[16:17], off
	s_waitcnt vmcnt(8)
	s_waitcnt lgkmcnt(0)
	s_barrier
	s_waitcnt lgkmcnt(0)
	v_mfma_f32_16x16x32_bf16 v[16:19], v[60:63], v[56:59], v[138:141]
	v_mfma_f32_16x16x32_bf16 v[80:83], v[184:187], v[92:95], v[16:19]
	v_mfma_f32_16x16x32_bf16 v[16:19], v[208:211], v[56:59], v[160:163]
	v_mfma_f32_16x16x32_bf16 v[84:87], v[212:215], v[92:95], v[16:19]
	v_mfma_f32_16x16x32_bf16 v[16:19], v[60:63], v[146:149], v[164:167]
	v_mfma_f32_16x16x32_bf16 v[48:51], v[184:187], v[150:153], v[16:19]
	v_mfma_f32_16x16x32_bf16 v[16:19], v[208:211], v[146:149], v[168:171]
	v_mfma_f32_16x16x32_bf16 v[52:55], v[212:215], v[150:153], v[16:19]
	v_mfma_f32_16x16x32_bf16 v[16:19], v[60:63], v[154:157], v[172:175]
	v_mfma_f32_16x16x32_bf16 v[20:23], v[208:211], v[154:157], v[176:179]
	v_mfma_f32_16x16x32_bf16 v[0:3], v[60:63], v[192:195], v[0:3]
	v_mfma_f32_16x16x32_bf16 v[4:7], v[208:211], v[192:195], v[4:7]
	v_mfma_f32_16x16x32_bf16 v[16:19], v[184:187], v[188:191], v[16:19]
	v_mfma_f32_16x16x32_bf16 v[20:23], v[212:215], v[188:191], v[20:23]
	v_mfma_f32_16x16x32_bf16 v[0:3], v[184:187], v[220:223], v[0:3]
	v_mfma_f32_16x16x32_bf16 v[4:7], v[212:215], v[220:223], v[4:7]
	v_mfma_f32_16x16x32_bf16 v[8:11], v[216:219], v[56:59], v[8:11]
	v_mfma_f32_16x16x32_bf16 v[88:91], v[224:227], v[92:95], v[8:11]
	v_mfma_f32_16x16x32_bf16 v[8:11], v[228:231], v[56:59], v[12:15]
	v_mfma_f32_16x16x32_bf16 v[92:95], v[232:235], v[92:95], v[8:11]
	v_mfma_f32_16x16x32_bf16 v[8:11], v[216:219], v[146:149], v[24:27]
	v_mfma_f32_16x16x32_bf16 v[56:59], v[224:227], v[150:153], v[8:11]
	v_mfma_f32_16x16x32_bf16 v[8:11], v[228:231], v[146:149], v[28:31]
	v_mfma_f32_16x16x32_bf16 v[60:63], v[232:235], v[150:153], v[8:11]
	v_mfma_f32_16x16x32_bf16 v[8:11], v[216:219], v[154:157], v[196:199]
	v_mfma_f32_16x16x32_bf16 v[24:27], v[224:227], v[188:191], v[8:11]
	v_mfma_f32_16x16x32_bf16 v[8:11], v[228:231], v[154:157], v[200:203]
	v_mfma_f32_16x16x32_bf16 v[28:31], v[232:235], v[188:191], v[8:11]
	v_mfma_f32_16x16x32_bf16 v[8:11], v[216:219], v[192:195], v[204:207]
	v_mfma_f32_16x16x32_bf16 v[12:15], v[228:231], v[192:195], v[180:183]
	v_mfma_f32_16x16x32_bf16 v[8:11], v[224:227], v[220:223], v[8:11]
	v_mfma_f32_16x16x32_bf16 v[12:15], v[232:235], v[220:223], v[12:15]
	s_barrier
	s_andn2_b64 vcc, exec, s[12:13]
	s_cbranch_vccnz .LBB0_739
	s_barrier

.LBB0_779:
	s_mov_b64 s[12:13], s[0:1]
	s_mov_b64 s[4:5], s[0:1]
	s_load_dwordx2 s[4:5], s[4:5], 0xb0
	s_load_dwordx2 s[12:13], s[12:13], 0xb8
	s_lshr_b32 s17, s15, 4
	s_ashr_i32 s8, s15, 8
	s_and_b32 s9, s17, 1
	s_lshl_b32 s16, s8, 1
	s_or_b32 s24, s16, s9
	s_ashr_i32 s25, s24, 31
	s_waitcnt lgkmcnt(0)
	v_lshl_add_u64 v[6:7], s[12:13], 0, v[0:1]
	s_lshl_b64 s[12:13], s[24:25], 16
	v_lshl_add_u64 v[6:7], v[6:7], 0, s[12:13]
	s_mov_b64 s[24:25], 0x2000
	global_load_dwordx4 v[34:37], v[6:7], off
	v_lshl_add_u64 v[6:7], v[6:7], 0, s[24:25]
	global_load_dwordx4 v[38:41], v[6:7], off
	v_lshl_add_u64 v[6:7], v[6:7], 0, s[24:25]
	global_load_dwordx4 v[42:45], v[6:7], off
	v_lshl_add_u64 v[6:7], v[6:7], 0, s[24:25]
	global_load_dwordx4 v[46:49], v[6:7], off
	v_lshl_add_u64 v[6:7], v[6:7], 0, s[24:25]
	global_load_dwordx4 v[50:53], v[6:7], off
	v_lshl_add_u64 v[6:7], v[6:7], 0, s[24:25]
	global_load_dwordx4 v[54:57], v[6:7], off
	v_lshl_add_u64 v[6:7], v[6:7], 0, s[24:25]
	global_load_dwordx4 v[60:63], v[6:7], off
	v_lshl_add_u64 v[6:7], v[6:7], 0, s[24:25]
	global_load_dwordx4 v[64:67], v[6:7], off
	v_ashrrev_i32_e32 v12, 5, v32
	v_and_b32_e32 v15, 0x7c, v22
	v_mul_lo_u32 v14, v12, s66
	v_lshlrev_b32_e32 v15, 2, v15
	v_add3_u32 v20, s67, v14, v15
	v_add3_u32 v14, 0, v14, v15
	s_lshl_b32 s10, s15, 6
	s_and_b32 s16, s10, 0x3c0
	s_lshl_b32 s10, s17, 7
	s_ashr_i32 s9, s8, 31
	s_and_b32 s17, s10, 0x780
	s_lshl_b64 s[12:13], s[8:9], 23
	s_add_u32 s4, s4, s12
	s_addc_u32 s5, s5, s13
	s_lshl_b32 s12, s16, 13
	s_add_u32 s4, s4, s12
	s_addc_u32 s5, s5, 0
	s_lshl_b32 s12, s17, 2
	s_add_u32 s4, s4, s12
	s_addc_u32 s5, s5, 0
	v_ashrrev_i32_e32 v13, 31, v12
	v_mov_b32_e32 v144, v15
	v_lshlrev_b64 v[8:9], 13, v[12:13]
	v_lshl_add_u64 v[8:9], s[4:5], 0, v[8:9]
	v_lshl_add_u64 v[8:9], v[8:9], 0, v[144:145]
	s_mov_b64 s[24:25], 0x20000
	global_load_dwordx4 v[10:13], v[8:9], off
	v_lshl_add_u64 v[8:9], v[8:9], 0, s[24:25]
	global_load_dwordx4 v[16:19], v[8:9], off
	v_lshl_add_u64 v[8:9], v[8:9], 0, s[24:25]
	global_load_dwordx4 v[26:29], v[8:9], off
	v_lshl_add_u64 v[8:9], v[8:9], 0, s[24:25]
	global_load_dwordx4 v[68:71], v[8:9], off
	s_waitcnt vmcnt(11)
	ds_write_b128 v14, v[34:37]
	s_waitcnt vmcnt(10)
	ds_write_b128 v14, v[38:41] offset:8448
	s_waitcnt vmcnt(9)
	ds_write_b128 v14, v[42:45] offset:16896
	s_waitcnt vmcnt(8)
	ds_write_b128 v14, v[46:49] offset:25344
	s_waitcnt vmcnt(7)
	ds_write_b128 v14, v[50:53] offset:33792
	s_waitcnt vmcnt(6)
	ds_write_b128 v14, v[54:57] offset:42240
	s_waitcnt vmcnt(5)
	ds_write_b128 v14, v[60:63] offset:50688
	s_waitcnt vmcnt(4)
	ds_write_b128 v14, v[64:67] offset:59136
	s_waitcnt vmcnt(3)
	ds_write_b128 v20, v[10:13]
	s_waitcnt vmcnt(2)
	ds_write_b128 v20, v[16:19] offset:8448
	s_waitcnt vmcnt(1)
	ds_write_b128 v20, v[26:29] offset:16896
	s_waitcnt vmcnt(0)
	ds_write_b128 v20, v[68:71] offset:25344
	v_mov_b32_e32 v14, 0
	s_waitcnt lgkmcnt(0)
	s_mov_b32 s4, 0
	v_mov_b32_e32 v15, v14
	v_mov_b32_e32 v20, v14
	v_mov_b32_e32 v21, v14
	v_mov_b32_e32 v16, v14
	v_mov_b32_e32 v17, v14
	v_mov_b32_e32 v18, v14
	v_mov_b32_e32 v19, v14
	v_mov_b32_e32 v10, v14
	v_mov_b32_e32 v11, v14
	v_mov_b32_e32 v12, v14
	v_mov_b32_e32 v13, v14
	v_mov_b32_e32 v6, v14
	v_mov_b32_e32 v7, v14
	v_mov_b32_e32 v8, v14
	v_mov_b32_e32 v9, v14
	s_barrier
